# combination: rq tile half LDS-DMA / half register staging in one batch, plus DPP-paired global_store_dword cross epilogue
# speedup vs baseline: 1.0076x; 1.0075x over previous
.LBB0_327:
	v_mov_b32_e32 v130, s67
	v_mov_b32_e32 v131, s66
	v_cndmask_b32_e32 v130, v130, v131, vcc
	v_lshl_add_u32 v168, v130, 7, v155
	v_mov_b32_e32 v153, v161
	v_mov_b32_e32 v192, v181
	v_mov_b32_e32 v190, v183
	v_mov_b32_e32 v191, v182
	v_mov_b32_e32 v166, v157
	v_mov_b32_e32 v130, v186
	v_mov_b32_e32 v131, v187
	v_ashrrev_i32_e32 v169, 31, v168
	v_readfirstlane_b32 s64, v130
	v_readfirstlane_b32 s65, v131
	v_lshlrev_b64 v[130:131], 11, v[168:169]
	v_mov_b32_e32 v167, v189
	s_barrier
	v_lshl_add_u64 v[228:229], s[64:65], 0, v[130:131]
	v_lshl_add_u64 v[228:229], v[228:229], 0, v[0:1]
	s_mov_b32 s6, 0xc640000
	s_mov_b32 s7, 0
	v_lshl_add_u64 v[228:229], v[228:229], 0, s[6:7]
	v_and_b32_e32 v230, 0xff, v189
	v_lshrrev_b32_e32 v231, 5, v230
	v_and_b32_e32 v232, 31, v230
	v_add_u32_e32 v233, 64, v231
	v_lshlrev_b32_e32 v233, 11, v233
	v_lshl_add_u32 v226, v232, 4, v233
	v_mov_b32_e32 v227, 0
	v_lshl_add_u64 v[226:227], v[228:229], 0, v[226:227]
	v_lshrrev_b32_e32 v233, 1, v231
	v_add_u32_e32 v233, 32, v233
	v_mul_u32_u24_e32 v233, 0x410, v233
	v_and_b32_e32 v231, 1, v231
	v_lshl_add_u32 v233, v231, 9, v233
	v_lshl_add_u32 v233, v232, 4, v233
	v_add_u32_e32 v230, v149, v233
	s_mov_b32 s6, 0x4000
	global_load_dwordx4 v[130:133], v[226:227], off
	v_lshl_add_u64 v[226:227], v[226:227], 0, s[6:7]
	global_load_dwordx4 v[134:137], v[226:227], off
	v_lshl_add_u64 v[226:227], v[226:227], 0, s[6:7]
	global_load_dwordx4 v[138:141], v[226:227], off
	v_lshl_add_u64 v[226:227], v[226:227], 0, s[6:7]
	global_load_dwordx4 v[142:145], v[226:227], off
	v_lshl_add_u64 v[226:227], v[226:227], 0, s[6:7]
	global_load_dwordx4 v[170:173], v[226:227], off
	v_lshl_add_u64 v[226:227], v[226:227], 0, s[6:7]
	global_load_dwordx4 v[194:197], v[226:227], off
	v_lshl_add_u64 v[226:227], v[226:227], 0, s[6:7]
	global_load_dwordx4 v[218:221], v[226:227], off
	v_lshl_add_u64 v[226:227], v[226:227], 0, s[6:7]
	global_load_dwordx4 v[222:225], v[226:227], off
	v_bfe_u32 v231, v189, 6, 2
	v_lshlrev_b32_e32 v231, 4, v231
	v_bfe_u32 v232, v189, 5, 1
	v_add_u32_e32 v231, v231, v232
	v_lshlrev_b32_e32 v231, 11, v231
	v_and_b32_e32 v232, 31, v189
	v_lshl_add_u32 v232, v232, 4, v231
	v_mov_b32_e32 v233, 0
	v_lshl_add_u64 v[228:229], v[228:229], 0, v[232:233]
	v_readfirstlane_b32 s6, v149
	v_readfirstlane_b32 s7, v189
	s_nop 3
	s_bfe_u32 s7, s7, 0x20006
	s_mul_i32 s7, s7, 0x2080
	s_add_u32 s6, s6, s7
	s_mov_b32 m0, s6
	s_mov_b32 s6, 0x1000
	s_mov_b32 s7, 0
	global_load_lds_dwordx4 v[228:229], off
	s_add_u32 m0, m0, 0x410
	v_lshl_add_u64 v[228:229], v[228:229], 0, s[6:7]
	global_load_lds_dwordx4 v[228:229], off
	s_add_u32 m0, m0, 0x410
	v_lshl_add_u64 v[228:229], v[228:229], 0, s[6:7]
	global_load_lds_dwordx4 v[228:229], off
	s_add_u32 m0, m0, 0x410
	v_lshl_add_u64 v[228:229], v[228:229], 0, s[6:7]
	global_load_lds_dwordx4 v[228:229], off
	s_add_u32 m0, m0, 0x410
	v_lshl_add_u64 v[228:229], v[228:229], 0, s[6:7]
	global_load_lds_dwordx4 v[228:229], off
	s_add_u32 m0, m0, 0x410
	v_lshl_add_u64 v[228:229], v[228:229], 0, s[6:7]
	global_load_lds_dwordx4 v[228:229], off
	s_add_u32 m0, m0, 0x410
	v_lshl_add_u64 v[228:229], v[228:229], 0, s[6:7]
	global_load_lds_dwordx4 v[228:229], off
	s_add_u32 m0, m0, 0x410
	v_lshl_add_u64 v[228:229], v[228:229], 0, s[6:7]
	global_load_lds_dwordx4 v[228:229], off
	s_waitcnt vmcnt(15)
	ds_write2_b64 v230, v[130:131], v[132:133] offset1:1
	s_waitcnt vmcnt(14)
	v_add_u32_e32 v231, 0x1040, v230
	ds_write2_b64 v231, v[134:135], v[136:137] offset1:1
	s_waitcnt vmcnt(13)
	v_add_u32_e32 v231, 0x2080, v230
	ds_write2_b64 v231, v[138:139], v[140:141] offset1:1
	s_waitcnt vmcnt(12)
	v_add_u32_e32 v231, 0x30c0, v230
	ds_write2_b64 v231, v[142:143], v[144:145] offset1:1
	s_waitcnt vmcnt(11)
	v_add_u32_e32 v231, 0x4100, v230
	ds_write2_b64 v231, v[170:171], v[172:173] offset1:1
	s_waitcnt vmcnt(10)
	v_add_u32_e32 v231, 0x5140, v230
	ds_write2_b64 v231, v[194:195], v[196:197] offset1:1
	s_waitcnt vmcnt(9)
	v_add_u32_e32 v231, 0x6180, v230
	ds_write2_b64 v231, v[218:219], v[220:221] offset1:1
	s_waitcnt vmcnt(8)
	v_add_u32_e32 v231, 0x71c0, v230
	ds_write2_b64 v231, v[222:223], v[224:225] offset1:1
	v_lshl_add_u64 v[210:211], s[64:65], 0, v[162:163]
	s_waitcnt vmcnt(0)
	s_waitcnt lgkmcnt(0)
	s_barrier
	v_ashrrev_i32_e32 v167, 31, v166
	v_lshl_add_u64 v[130:131], v[166:167], 1, v[210:211]
	s_mov_b64 s[6:7], 0x8640000
	v_lshl_add_u64 v[170:171], v[130:131], 0, s[6:7]
	v_add_u32_e32 v250, 0x4000, v178
	ds_read2_b64 v[194:197], v178 offset0:0 offset1:2
	ds_read2_b64 v[218:221], v250 offset0:32 offset1:34
	ds_read2_b64 v[222:225], v178 offset0:4 offset1:6
	ds_read2_b64 v[226:229], v250 offset0:36 offset1:38
	s_nop 0
	v_cvt_pk_bf16_f32 v230, v2, v3
	v_cvt_pk_bf16_f32 v231, v4, v5
	v_cvt_pk_bf16_f32 v232, v6, v7
	v_cvt_pk_bf16_f32 v233, v8, v9
	s_waitcnt lgkmcnt(2)
	s_nop 1
	v_mfma_f32_32x32x16_bf16 v[130:145], v[194:197], v[230:233], 0
	v_mfma_f32_32x32x16_bf16 v[234:249], v[218:221], v[230:233], 0
	ds_read2_b64 v[194:197], v178 offset0:8 offset1:10
	ds_read2_b64 v[218:221], v250 offset0:40 offset1:42
	s_nop 0
	v_cvt_pk_bf16_f32 v230, v10, v11
	v_cvt_pk_bf16_f32 v231, v12, v13
	v_cvt_pk_bf16_f32 v232, v14, v15
	v_cvt_pk_bf16_f32 v233, v16, v17
	s_waitcnt lgkmcnt(2)
	s_nop 1
	v_mfma_f32_32x32x16_bf16 v[130:145], v[222:225], v[230:233], v[130:145]
	v_mfma_f32_32x32x16_bf16 v[234:249], v[226:229], v[230:233], v[234:249]
	ds_read2_b64 v[222:225], v178 offset0:12 offset1:14
	ds_read2_b64 v[226:229], v250 offset0:44 offset1:46
	s_nop 0
	v_cvt_pk_bf16_f32 v230, v18, v19
	v_cvt_pk_bf16_f32 v231, v20, v21
	v_cvt_pk_bf16_f32 v232, v22, v23
	v_cvt_pk_bf16_f32 v233, v24, v25
	s_waitcnt lgkmcnt(2)
	s_nop 1
	v_mfma_f32_32x32x16_bf16 v[130:145], v[194:197], v[230:233], v[130:145]
	v_mfma_f32_32x32x16_bf16 v[234:249], v[218:221], v[230:233], v[234:249]
	ds_read2_b64 v[194:197], v178 offset0:16 offset1:18
	ds_read2_b64 v[218:221], v250 offset0:48 offset1:50
	s_nop 0
	v_cvt_pk_bf16_f32 v230, v26, v27
	v_cvt_pk_bf16_f32 v231, v28, v29
	v_cvt_pk_bf16_f32 v232, v30, v31
	v_cvt_pk_bf16_f32 v233, v32, v33
	s_waitcnt lgkmcnt(2)
	s_nop 1
	v_mfma_f32_32x32x16_bf16 v[130:145], v[222:225], v[230:233], v[130:145]
	v_mfma_f32_32x32x16_bf16 v[234:249], v[226:229], v[230:233], v[234:249]
	ds_read2_b64 v[222:225], v178 offset0:20 offset1:22
	ds_read2_b64 v[226:229], v250 offset0:52 offset1:54
	s_nop 0
	v_cvt_pk_bf16_f32 v230, v34, v35
	v_cvt_pk_bf16_f32 v231, v36, v37
	v_cvt_pk_bf16_f32 v232, v38, v39
	v_cvt_pk_bf16_f32 v233, v40, v41
	s_waitcnt lgkmcnt(2)
	s_nop 1
	v_mfma_f32_32x32x16_bf16 v[130:145], v[194:197], v[230:233], v[130:145]
	v_mfma_f32_32x32x16_bf16 v[234:249], v[218:221], v[230:233], v[234:249]
	ds_read2_b64 v[194:197], v178 offset0:24 offset1:26
	ds_read2_b64 v[218:221], v250 offset0:56 offset1:58
	s_nop 0
	v_cvt_pk_bf16_f32 v230, v42, v43
	v_cvt_pk_bf16_f32 v231, v44, v45
	v_cvt_pk_bf16_f32 v232, v46, v47
	v_cvt_pk_bf16_f32 v233, v48, v49
	s_waitcnt lgkmcnt(2)
	s_nop 1
	v_mfma_f32_32x32x16_bf16 v[130:145], v[222:225], v[230:233], v[130:145]
	v_mfma_f32_32x32x16_bf16 v[234:249], v[226:229], v[230:233], v[234:249]
	ds_read2_b64 v[222:225], v178 offset0:28 offset1:30
	ds_read2_b64 v[226:229], v250 offset0:60 offset1:62
	s_nop 0
	v_cvt_pk_bf16_f32 v230, v50, v51
	v_cvt_pk_bf16_f32 v231, v52, v53
	v_cvt_pk_bf16_f32 v232, v54, v55
	v_cvt_pk_bf16_f32 v233, v56, v57
	s_waitcnt lgkmcnt(2)
	s_nop 1
	v_mfma_f32_32x32x16_bf16 v[130:145], v[194:197], v[230:233], v[130:145]
	v_mfma_f32_32x32x16_bf16 v[234:249], v[218:221], v[230:233], v[234:249]
	ds_read2_b64 v[194:197], v178 offset0:32 offset1:34
	ds_read2_b64 v[218:221], v250 offset0:64 offset1:66
	s_nop 0
	v_cvt_pk_bf16_f32 v230, v58, v59
	v_cvt_pk_bf16_f32 v231, v60, v61
	v_cvt_pk_bf16_f32 v232, v62, v63
	v_cvt_pk_bf16_f32 v233, v64, v65
	s_waitcnt lgkmcnt(2)
	s_nop 1
	v_mfma_f32_32x32x16_bf16 v[130:145], v[222:225], v[230:233], v[130:145]
	v_mfma_f32_32x32x16_bf16 v[234:249], v[226:229], v[230:233], v[234:249]
	ds_read2_b64 v[222:225], v178 offset0:36 offset1:38
	ds_read2_b64 v[226:229], v250 offset0:68 offset1:70
	s_nop 0
	v_cvt_pk_bf16_f32 v230, v66, v67
	v_cvt_pk_bf16_f32 v231, v68, v69
	v_cvt_pk_bf16_f32 v232, v70, v71
	v_cvt_pk_bf16_f32 v233, v72, v73
	s_waitcnt lgkmcnt(2)
	s_nop 1
	v_mfma_f32_32x32x16_bf16 v[130:145], v[194:197], v[230:233], v[130:145]
	v_mfma_f32_32x32x16_bf16 v[234:249], v[218:221], v[230:233], v[234:249]
	ds_read2_b64 v[194:197], v178 offset0:40 offset1:42
	ds_read2_b64 v[218:221], v250 offset0:72 offset1:74
	s_nop 0
	v_cvt_pk_bf16_f32 v230, v74, v75
	v_cvt_pk_bf16_f32 v231, v76, v77
	v_cvt_pk_bf16_f32 v232, v78, v79
	v_cvt_pk_bf16_f32 v233, v80, v81
	s_waitcnt lgkmcnt(2)
	s_nop 1
	v_mfma_f32_32x32x16_bf16 v[130:145], v[222:225], v[230:233], v[130:145]
	v_mfma_f32_32x32x16_bf16 v[234:249], v[226:229], v[230:233], v[234:249]
	ds_read2_b64 v[222:225], v178 offset0:44 offset1:46
	ds_read2_b64 v[226:229], v250 offset0:76 offset1:78
	s_nop 0
	v_cvt_pk_bf16_f32 v230, v82, v83
	v_cvt_pk_bf16_f32 v231, v84, v85
	v_cvt_pk_bf16_f32 v232, v86, v87
	v_cvt_pk_bf16_f32 v233, v88, v89
	s_waitcnt lgkmcnt(2)
	s_nop 1
	v_mfma_f32_32x32x16_bf16 v[130:145], v[194:197], v[230:233], v[130:145]
	v_mfma_f32_32x32x16_bf16 v[234:249], v[218:221], v[230:233], v[234:249]
	ds_read2_b64 v[194:197], v178 offset0:48 offset1:50
	ds_read2_b64 v[218:221], v250 offset0:80 offset1:82
	s_nop 0
	v_cvt_pk_bf16_f32 v230, v90, v91
	v_cvt_pk_bf16_f32 v231, v92, v93
	v_cvt_pk_bf16_f32 v232, v94, v95
	v_cvt_pk_bf16_f32 v233, v96, v97
	s_waitcnt lgkmcnt(2)
	s_nop 1
	v_mfma_f32_32x32x16_bf16 v[130:145], v[222:225], v[230:233], v[130:145]
	v_mfma_f32_32x32x16_bf16 v[234:249], v[226:229], v[230:233], v[234:249]
	ds_read2_b64 v[222:225], v178 offset0:52 offset1:54
	ds_read2_b64 v[226:229], v250 offset0:84 offset1:86
	s_nop 0
	v_cvt_pk_bf16_f32 v230, v98, v99
	v_cvt_pk_bf16_f32 v231, v100, v101
	v_cvt_pk_bf16_f32 v232, v102, v103
	v_cvt_pk_bf16_f32 v233, v104, v105
	s_waitcnt lgkmcnt(2)
	s_nop 1
	v_mfma_f32_32x32x16_bf16 v[130:145], v[194:197], v[230:233], v[130:145]
	v_mfma_f32_32x32x16_bf16 v[234:249], v[218:221], v[230:233], v[234:249]
	ds_read2_b64 v[194:197], v178 offset0:56 offset1:58
	ds_read2_b64 v[218:221], v250 offset0:88 offset1:90
	s_nop 0
	v_cvt_pk_bf16_f32 v230, v106, v107
	v_cvt_pk_bf16_f32 v231, v108, v109
	v_cvt_pk_bf16_f32 v232, v110, v111
	v_cvt_pk_bf16_f32 v233, v112, v113
	s_waitcnt lgkmcnt(2)
	s_nop 1
	v_mfma_f32_32x32x16_bf16 v[130:145], v[222:225], v[230:233], v[130:145]
	v_mfma_f32_32x32x16_bf16 v[234:249], v[226:229], v[230:233], v[234:249]
	ds_read2_b64 v[222:225], v178 offset0:60 offset1:62
	ds_read2_b64 v[226:229], v250 offset0:92 offset1:94
	s_nop 0
	v_cvt_pk_bf16_f32 v230, v114, v115
	v_cvt_pk_bf16_f32 v231, v116, v117
	v_cvt_pk_bf16_f32 v232, v118, v119
	v_cvt_pk_bf16_f32 v233, v120, v121
	s_waitcnt lgkmcnt(2)
	s_nop 1
	v_mfma_f32_32x32x16_bf16 v[130:145], v[194:197], v[230:233], v[130:145]
	v_mfma_f32_32x32x16_bf16 v[234:249], v[218:221], v[230:233], v[234:249]
	s_nop 0
	v_cvt_pk_bf16_f32 v230, v122, v123
	v_cvt_pk_bf16_f32 v231, v124, v125
	v_cvt_pk_bf16_f32 v232, v126, v127
	v_cvt_pk_bf16_f32 v233, v128, v129
	s_waitcnt lgkmcnt(0)
	s_nop 1
	v_mfma_f32_32x32x16_bf16 v[130:145], v[222:225], v[230:233], v[130:145]
	v_mfma_f32_32x32x16_bf16 v[234:249], v[226:229], v[230:233], v[234:249]
	v_or_b32_e32 v172, v168, v174
	v_ashrrev_i32_e32 v173, 31, v172
	v_lshlrev_b64 v[172:173], 12, v[172:173]
	s_mov_b32 s100, 0xaaaaaaaa
	s_mov_b32 s101, 0xaaaaaaaa
	v_and_b32_e32 v220, 1, v189
	v_mul_u32_u24_e32 v220, 0xffe, v220
	v_mov_b32_e32 v221, 0
	v_lshl_add_u64 v[218:219], v[170:171], 0, v[172:173]
	v_lshl_add_u64 v[218:219], v[218:219], 0, v[220:221]
	s_mov_b32 s7, 0
	s_nop 7
	v_fma_f32 v222, 0, v192, v153
	v_add_f32_e32 v223, v153, v192
	v_exp_f32_e32 v222, v222
	v_exp_f32_e32 v223, v223
	s_nop 0
	v_mul_f32_e32 v222, v222, v130
	v_mul_f32_e32 v223, v223, v131
	s_nop 1
	v_mov_b32_dpp v224, v222 quad_perm:[1,0,3,2] row_mask:0xf bank_mask:0xf
	v_mov_b32_dpp v225, v223 quad_perm:[1,0,3,2] row_mask:0xf bank_mask:0xf
	v_cndmask_b32_e64 v226, v222, v225, s[100:101]
	v_cndmask_b32_e64 v227, v224, v223, s[100:101]
	v_cvt_pk_bf16_f32 v226, v226, v227
	s_mov_b32 s6, 0x0
	v_lshl_add_u64 v[228:229], v[218:219], 0, s[6:7]
	global_store_dword v[228:229], v226, off
	v_fma_f32 v222, 2.0, v192, v153
	v_fmamk_f32 v223, v192, 0x40400000, v153
	v_exp_f32_e32 v222, v222
	v_exp_f32_e32 v223, v223
	s_nop 0
	v_mul_f32_e32 v222, v222, v132
	v_mul_f32_e32 v223, v223, v133
	s_nop 1
	v_mov_b32_dpp v224, v222 quad_perm:[1,0,3,2] row_mask:0xf bank_mask:0xf
	v_mov_b32_dpp v225, v223 quad_perm:[1,0,3,2] row_mask:0xf bank_mask:0xf
	v_cndmask_b32_e64 v226, v222, v225, s[100:101]
	v_cndmask_b32_e64 v227, v224, v223, s[100:101]
	v_cvt_pk_bf16_f32 v226, v226, v227
	s_mov_b32 s6, 0x2000
	v_lshl_add_u64 v[228:229], v[218:219], 0, s[6:7]
	global_store_dword v[228:229], v226, off
	v_fmamk_f32 v222, v192, 0x41000000, v153
	v_fmamk_f32 v223, v192, 0x41100000, v153
	v_exp_f32_e32 v222, v222
	v_exp_f32_e32 v223, v223
	s_nop 0
	v_mul_f32_e32 v222, v222, v134
	v_mul_f32_e32 v223, v223, v135
	s_nop 1
	v_mov_b32_dpp v224, v222 quad_perm:[1,0,3,2] row_mask:0xf bank_mask:0xf
	v_mov_b32_dpp v225, v223 quad_perm:[1,0,3,2] row_mask:0xf bank_mask:0xf
	v_cndmask_b32_e64 v226, v222, v225, s[100:101]
	v_cndmask_b32_e64 v227, v224, v223, s[100:101]
	v_cvt_pk_bf16_f32 v226, v226, v227
	s_mov_b32 s6, 0x8000
	v_lshl_add_u64 v[228:229], v[218:219], 0, s[6:7]
	global_store_dword v[228:229], v226, off
	v_fmamk_f32 v222, v192, 0x41200000, v153
	v_fmamk_f32 v223, v192, 0x41300000, v153
	v_exp_f32_e32 v222, v222
	v_exp_f32_e32 v223, v223
	s_nop 0
	v_mul_f32_e32 v222, v222, v136
	v_mul_f32_e32 v223, v223, v137
	s_nop 1
	v_mov_b32_dpp v224, v222 quad_perm:[1,0,3,2] row_mask:0xf bank_mask:0xf
	v_mov_b32_dpp v225, v223 quad_perm:[1,0,3,2] row_mask:0xf bank_mask:0xf
	v_cndmask_b32_e64 v226, v222, v225, s[100:101]
	v_cndmask_b32_e64 v227, v224, v223, s[100:101]
	v_cvt_pk_bf16_f32 v226, v226, v227
	s_mov_b32 s6, 0xa000
	v_lshl_add_u64 v[228:229], v[218:219], 0, s[6:7]
	global_store_dword v[228:229], v226, off
	v_fmamk_f32 v222, v192, 0x41800000, v153
	v_fmamk_f32 v223, v192, 0x41880000, v153
	v_exp_f32_e32 v222, v222
	v_exp_f32_e32 v223, v223
	s_nop 0
	v_mul_f32_e32 v222, v222, v138
	v_mul_f32_e32 v223, v223, v139
	s_nop 1
	v_mov_b32_dpp v224, v222 quad_perm:[1,0,3,2] row_mask:0xf bank_mask:0xf
	v_mov_b32_dpp v225, v223 quad_perm:[1,0,3,2] row_mask:0xf bank_mask:0xf
	v_cndmask_b32_e64 v226, v222, v225, s[100:101]
	v_cndmask_b32_e64 v227, v224, v223, s[100:101]
	v_cvt_pk_bf16_f32 v226, v226, v227
	s_mov_b32 s6, 0x10000
	v_lshl_add_u64 v[228:229], v[218:219], 0, s[6:7]
	global_store_dword v[228:229], v226, off
	v_fmamk_f32 v222, v192, 0x41900000, v153
	v_fmamk_f32 v223, v192, 0x41980000, v153
	v_exp_f32_e32 v222, v222
	v_exp_f32_e32 v223, v223
	s_nop 0
	v_mul_f32_e32 v222, v222, v140
	v_mul_f32_e32 v223, v223, v141
	s_nop 1
	v_mov_b32_dpp v224, v222 quad_perm:[1,0,3,2] row_mask:0xf bank_mask:0xf
	v_mov_b32_dpp v225, v223 quad_perm:[1,0,3,2] row_mask:0xf bank_mask:0xf
	v_cndmask_b32_e64 v226, v222, v225, s[100:101]
	v_cndmask_b32_e64 v227, v224, v223, s[100:101]
	v_cvt_pk_bf16_f32 v226, v226, v227
	s_mov_b32 s6, 0x12000
	v_lshl_add_u64 v[228:229], v[218:219], 0, s[6:7]
	global_store_dword v[228:229], v226, off
	v_fmamk_f32 v222, v192, 0x41c00000, v153
	v_fmamk_f32 v223, v192, 0x41c80000, v153
	v_exp_f32_e32 v222, v222
	v_exp_f32_e32 v223, v223
	s_nop 0
	v_mul_f32_e32 v222, v222, v142
	v_mul_f32_e32 v223, v223, v143
	s_nop 1
	v_mov_b32_dpp v224, v222 quad_perm:[1,0,3,2] row_mask:0xf bank_mask:0xf
	v_mov_b32_dpp v225, v223 quad_perm:[1,0,3,2] row_mask:0xf bank_mask:0xf
	v_cndmask_b32_e64 v226, v222, v225, s[100:101]
	v_cndmask_b32_e64 v227, v224, v223, s[100:101]
	v_cvt_pk_bf16_f32 v226, v226, v227
	s_mov_b32 s6, 0x18000
	v_lshl_add_u64 v[228:229], v[218:219], 0, s[6:7]
	global_store_dword v[228:229], v226, off
	v_fmamk_f32 v222, v192, 0x41d00000, v153
	v_fmamk_f32 v223, v192, 0x41d80000, v153
	v_exp_f32_e32 v222, v222
	v_exp_f32_e32 v223, v223
	s_nop 0
	v_mul_f32_e32 v222, v222, v144
	v_mul_f32_e32 v223, v223, v145
	s_nop 1
	v_mov_b32_dpp v224, v222 quad_perm:[1,0,3,2] row_mask:0xf bank_mask:0xf
	v_mov_b32_dpp v225, v223 quad_perm:[1,0,3,2] row_mask:0xf bank_mask:0xf
	v_cndmask_b32_e64 v226, v222, v225, s[100:101]
	v_cndmask_b32_e64 v227, v224, v223, s[100:101]
	v_cvt_pk_bf16_f32 v226, v226, v227
	s_mov_b32 s6, 0x1a000
	v_lshl_add_u64 v[228:229], v[218:219], 0, s[6:7]
	global_store_dword v[228:229], v226, off
	v_mov_b32_e32 v130, v234
	v_mov_b32_e32 v131, v235
	v_mov_b32_e32 v132, v236
	v_mov_b32_e32 v133, v237
	v_mov_b32_e32 v134, v238
	v_mov_b32_e32 v135, v239
	v_mov_b32_e32 v136, v240
	v_mov_b32_e32 v137, v241
	v_mov_b32_e32 v138, v242
	v_mov_b32_e32 v139, v243
	v_mov_b32_e32 v140, v244
	v_mov_b32_e32 v141, v245
	v_mov_b32_e32 v142, v246
	v_mov_b32_e32 v143, v247
	v_mov_b32_e32 v144, v248
	v_mov_b32_e32 v145, v249
	s_mov_b32 s100, 0xaaaaaaaa
	s_mov_b32 s101, 0xaaaaaaaa
	v_and_b32_e32 v220, 1, v189
	v_mul_u32_u24_e32 v220, 0xffe, v220
	v_mov_b32_e32 v221, 0
	v_lshl_add_u64 v[218:219], v[170:171], 0, v[172:173]
	v_lshl_add_u64 v[218:219], v[218:219], 0, v[220:221]
	s_mov_b32 s7, 0
	s_nop 7
	v_fmamk_f32 v222, v192, 0x42000000, v153
	v_fmamk_f32 v223, v192, 0x42040000, v153
	v_exp_f32_e32 v222, v222
	v_exp_f32_e32 v223, v223
	s_nop 0
	v_mul_f32_e32 v222, v222, v130
	v_mul_f32_e32 v223, v223, v131
	s_nop 1
	v_mov_b32_dpp v224, v222 quad_perm:[1,0,3,2] row_mask:0xf bank_mask:0xf
	v_mov_b32_dpp v225, v223 quad_perm:[1,0,3,2] row_mask:0xf bank_mask:0xf
	v_cndmask_b32_e64 v226, v222, v225, s[100:101]
	v_cndmask_b32_e64 v227, v224, v223, s[100:101]
	v_cvt_pk_bf16_f32 v226, v226, v227
	s_mov_b32 s6, 0x20000
	v_lshl_add_u64 v[228:229], v[218:219], 0, s[6:7]
	global_store_dword v[228:229], v226, off
	v_fmamk_f32 v222, v192, 0x42080000, v153
	v_fmamk_f32 v223, v192, 0x420c0000, v153
	v_exp_f32_e32 v222, v222
	v_exp_f32_e32 v223, v223
	s_nop 0
	v_mul_f32_e32 v222, v222, v132
	v_mul_f32_e32 v223, v223, v133
	s_nop 1
	v_mov_b32_dpp v224, v222 quad_perm:[1,0,3,2] row_mask:0xf bank_mask:0xf
	v_mov_b32_dpp v225, v223 quad_perm:[1,0,3,2] row_mask:0xf bank_mask:0xf
	v_cndmask_b32_e64 v226, v222, v225, s[100:101]
	v_cndmask_b32_e64 v227, v224, v223, s[100:101]
	v_cvt_pk_bf16_f32 v226, v226, v227
	s_mov_b32 s6, 0x22000
	v_lshl_add_u64 v[228:229], v[218:219], 0, s[6:7]
	global_store_dword v[228:229], v226, off
	v_fmamk_f32 v222, v192, 0x42200000, v153
	v_fmamk_f32 v223, v192, 0x42240000, v153
	v_exp_f32_e32 v222, v222
	v_exp_f32_e32 v223, v223
	s_nop 0
	v_mul_f32_e32 v222, v222, v134
	v_mul_f32_e32 v223, v223, v135
	s_nop 1
	v_mov_b32_dpp v224, v222 quad_perm:[1,0,3,2] row_mask:0xf bank_mask:0xf
	v_mov_b32_dpp v225, v223 quad_perm:[1,0,3,2] row_mask:0xf bank_mask:0xf
	v_cndmask_b32_e64 v226, v222, v225, s[100:101]
	v_cndmask_b32_e64 v227, v224, v223, s[100:101]
	v_cvt_pk_bf16_f32 v226, v226, v227
	s_mov_b32 s6, 0x28000
	v_lshl_add_u64 v[228:229], v[218:219], 0, s[6:7]
	global_store_dword v[228:229], v226, off
	v_fmamk_f32 v222, v192, 0x42280000, v153
	v_fmamk_f32 v223, v192, 0x422c0000, v153
	v_exp_f32_e32 v222, v222
	v_exp_f32_e32 v223, v223
	s_nop 0
	v_mul_f32_e32 v222, v222, v136
	v_mul_f32_e32 v223, v223, v137
	s_nop 1
	v_mov_b32_dpp v224, v222 quad_perm:[1,0,3,2] row_mask:0xf bank_mask:0xf
	v_mov_b32_dpp v225, v223 quad_perm:[1,0,3,2] row_mask:0xf bank_mask:0xf
	v_cndmask_b32_e64 v226, v222, v225, s[100:101]
	v_cndmask_b32_e64 v227, v224, v223, s[100:101]
	v_cvt_pk_bf16_f32 v226, v226, v227
	s_mov_b32 s6, 0x2a000
	v_lshl_add_u64 v[228:229], v[218:219], 0, s[6:7]
	global_store_dword v[228:229], v226, off
	v_fmamk_f32 v222, v192, 0x42400000, v153
	v_fmamk_f32 v223, v192, 0x42440000, v153
	v_exp_f32_e32 v222, v222
	v_exp_f32_e32 v223, v223
	s_nop 0
	v_mul_f32_e32 v222, v222, v138
	v_mul_f32_e32 v223, v223, v139
	s_nop 1
	v_mov_b32_dpp v224, v222 quad_perm:[1,0,3,2] row_mask:0xf bank_mask:0xf
	v_mov_b32_dpp v225, v223 quad_perm:[1,0,3,2] row_mask:0xf bank_mask:0xf
	v_cndmask_b32_e64 v226, v222, v225, s[100:101]
	v_cndmask_b32_e64 v227, v224, v223, s[100:101]
	v_cvt_pk_bf16_f32 v226, v226, v227
	s_mov_b32 s6, 0x30000
	v_lshl_add_u64 v[228:229], v[218:219], 0, s[6:7]
	global_store_dword v[228:229], v226, off
	v_fmamk_f32 v222, v192, 0x42480000, v153
	v_fmamk_f32 v223, v192, 0x424c0000, v153
	v_exp_f32_e32 v222, v222
	v_exp_f32_e32 v223, v223
	s_nop 0
	v_mul_f32_e32 v222, v222, v140
	v_mul_f32_e32 v223, v223, v141
	s_nop 1
	v_mov_b32_dpp v224, v222 quad_perm:[1,0,3,2] row_mask:0xf bank_mask:0xf
	v_mov_b32_dpp v225, v223 quad_perm:[1,0,3,2] row_mask:0xf bank_mask:0xf
	v_cndmask_b32_e64 v226, v222, v225, s[100:101]
	v_cndmask_b32_e64 v227, v224, v223, s[100:101]
	v_cvt_pk_bf16_f32 v226, v226, v227
	s_mov_b32 s6, 0x32000
	v_lshl_add_u64 v[228:229], v[218:219], 0, s[6:7]
	global_store_dword v[228:229], v226, off
	v_fmamk_f32 v222, v192, 0x42600000, v153
	v_fmamk_f32 v223, v192, 0x42640000, v153
	v_exp_f32_e32 v222, v222
	v_exp_f32_e32 v223, v223
	s_nop 0
	v_mul_f32_e32 v222, v222, v142
	v_mul_f32_e32 v223, v223, v143
	s_nop 1
	v_mov_b32_dpp v224, v222 quad_perm:[1,0,3,2] row_mask:0xf bank_mask:0xf
	v_mov_b32_dpp v225, v223 quad_perm:[1,0,3,2] row_mask:0xf bank_mask:0xf
	v_cndmask_b32_e64 v226, v222, v225, s[100:101]
	v_cndmask_b32_e64 v227, v224, v223, s[100:101]
	v_cvt_pk_bf16_f32 v226, v226, v227
	s_mov_b32 s6, 0x38000
	v_lshl_add_u64 v[228:229], v[218:219], 0, s[6:7]
	global_store_dword v[228:229], v226, off
	v_fmamk_f32 v222, v192, 0x42680000, v153
	v_fmamk_f32 v223, v192, 0x426c0000, v153
	v_exp_f32_e32 v222, v222
	v_exp_f32_e32 v223, v223
	s_nop 0
	v_mul_f32_e32 v222, v222, v144
	v_mul_f32_e32 v223, v223, v145
	s_nop 1
	v_mov_b32_dpp v224, v222 quad_perm:[1,0,3,2] row_mask:0xf bank_mask:0xf
	v_mov_b32_dpp v225, v223 quad_perm:[1,0,3,2] row_mask:0xf bank_mask:0xf
	v_cndmask_b32_e64 v226, v222, v225, s[100:101]
	v_cndmask_b32_e64 v227, v224, v223, s[100:101]
	v_cvt_pk_bf16_f32 v226, v226, v227
	s_mov_b32 s6, 0x3a000
	v_lshl_add_u64 v[228:229], v[218:219], 0, s[6:7]
	global_store_dword v[228:229], v226, off
	v_add_u32_e32 v250, 0xc000, v178
	v_add_u32_e32 v251, 0x8000, v178
	ds_read2_b64 v[194:197], v251 offset0:64 offset1:66
	ds_read2_b64 v[218:221], v250 offset0:96 offset1:98
	ds_read2_b64 v[222:225], v251 offset0:68 offset1:70
	ds_read2_b64 v[226:229], v250 offset0:100 offset1:102
	s_nop 0
	v_cvt_pk_bf16_f32 v230, v2, v3
	v_cvt_pk_bf16_f32 v231, v4, v5
	v_cvt_pk_bf16_f32 v232, v6, v7
	v_cvt_pk_bf16_f32 v233, v8, v9
	s_waitcnt lgkmcnt(2)
	s_nop 1
	v_mfma_f32_32x32x16_bf16 v[130:145], v[194:197], v[230:233], 0
	v_mfma_f32_32x32x16_bf16 v[234:249], v[218:221], v[230:233], 0
	ds_read2_b64 v[194:197], v251 offset0:72 offset1:74
	ds_read2_b64 v[218:221], v250 offset0:104 offset1:106
	s_nop 0
	v_cvt_pk_bf16_f32 v230, v10, v11
	v_cvt_pk_bf16_f32 v231, v12, v13
	v_cvt_pk_bf16_f32 v232, v14, v15
	v_cvt_pk_bf16_f32 v233, v16, v17
	s_waitcnt lgkmcnt(2)
	s_nop 1
	v_mfma_f32_32x32x16_bf16 v[130:145], v[222:225], v[230:233], v[130:145]
	v_mfma_f32_32x32x16_bf16 v[234:249], v[226:229], v[230:233], v[234:249]
	ds_read2_b64 v[222:225], v251 offset0:76 offset1:78
	ds_read2_b64 v[226:229], v250 offset0:108 offset1:110
	s_nop 0
	v_cvt_pk_bf16_f32 v230, v18, v19
	v_cvt_pk_bf16_f32 v231, v20, v21
	v_cvt_pk_bf16_f32 v232, v22, v23
	v_cvt_pk_bf16_f32 v233, v24, v25
	s_waitcnt lgkmcnt(2)
	s_nop 1
	v_mfma_f32_32x32x16_bf16 v[130:145], v[194:197], v[230:233], v[130:145]
	v_mfma_f32_32x32x16_bf16 v[234:249], v[218:221], v[230:233], v[234:249]
	ds_read2_b64 v[194:197], v251 offset0:80 offset1:82
	ds_read2_b64 v[218:221], v250 offset0:112 offset1:114
	s_nop 0
	v_cvt_pk_bf16_f32 v230, v26, v27
	v_cvt_pk_bf16_f32 v231, v28, v29
	v_cvt_pk_bf16_f32 v232, v30, v31
	v_cvt_pk_bf16_f32 v233, v32, v33
	s_waitcnt lgkmcnt(2)
	s_nop 1
	v_mfma_f32_32x32x16_bf16 v[130:145], v[222:225], v[230:233], v[130:145]
	v_mfma_f32_32x32x16_bf16 v[234:249], v[226:229], v[230:233], v[234:249]
	ds_read2_b64 v[222:225], v251 offset0:84 offset1:86
	ds_read2_b64 v[226:229], v250 offset0:116 offset1:118
	s_nop 0
	v_cvt_pk_bf16_f32 v230, v34, v35
	v_cvt_pk_bf16_f32 v231, v36, v37
	v_cvt_pk_bf16_f32 v232, v38, v39
	v_cvt_pk_bf16_f32 v233, v40, v41
	s_waitcnt lgkmcnt(2)
	s_nop 1
	v_mfma_f32_32x32x16_bf16 v[130:145], v[194:197], v[230:233], v[130:145]
	v_mfma_f32_32x32x16_bf16 v[234:249], v[218:221], v[230:233], v[234:249]
	ds_read2_b64 v[194:197], v251 offset0:88 offset1:90
	ds_read2_b64 v[218:221], v250 offset0:120 offset1:122
	s_nop 0
	v_cvt_pk_bf16_f32 v230, v42, v43
	v_cvt_pk_bf16_f32 v231, v44, v45
	v_cvt_pk_bf16_f32 v232, v46, v47
	v_cvt_pk_bf16_f32 v233, v48, v49
	s_waitcnt lgkmcnt(2)
	s_nop 1
	v_mfma_f32_32x32x16_bf16 v[130:145], v[222:225], v[230:233], v[130:145]
	v_mfma_f32_32x32x16_bf16 v[234:249], v[226:229], v[230:233], v[234:249]
	ds_read2_b64 v[222:225], v251 offset0:92 offset1:94
	ds_read2_b64 v[226:229], v250 offset0:124 offset1:126
	s_nop 0
	v_cvt_pk_bf16_f32 v230, v50, v51
	v_cvt_pk_bf16_f32 v231, v52, v53
	v_cvt_pk_bf16_f32 v232, v54, v55
	v_cvt_pk_bf16_f32 v233, v56, v57
	s_waitcnt lgkmcnt(2)
	s_nop 1
	v_mfma_f32_32x32x16_bf16 v[130:145], v[194:197], v[230:233], v[130:145]
	v_mfma_f32_32x32x16_bf16 v[234:249], v[218:221], v[230:233], v[234:249]
	ds_read2_b64 v[194:197], v251 offset0:96 offset1:98
	ds_read2_b64 v[218:221], v250 offset0:128 offset1:130
	s_nop 0
	v_cvt_pk_bf16_f32 v230, v58, v59
	v_cvt_pk_bf16_f32 v231, v60, v61
	v_cvt_pk_bf16_f32 v232, v62, v63
	v_cvt_pk_bf16_f32 v233, v64, v65
	s_waitcnt lgkmcnt(2)
	s_nop 1
	v_mfma_f32_32x32x16_bf16 v[130:145], v[222:225], v[230:233], v[130:145]
	v_mfma_f32_32x32x16_bf16 v[234:249], v[226:229], v[230:233], v[234:249]
	ds_read2_b64 v[222:225], v251 offset0:100 offset1:102
	ds_read2_b64 v[226:229], v250 offset0:132 offset1:134
	s_nop 0
	v_cvt_pk_bf16_f32 v230, v66, v67
	v_cvt_pk_bf16_f32 v231, v68, v69
	v_cvt_pk_bf16_f32 v232, v70, v71
	v_cvt_pk_bf16_f32 v233, v72, v73
	s_waitcnt lgkmcnt(2)
	s_nop 1
	v_mfma_f32_32x32x16_bf16 v[130:145], v[194:197], v[230:233], v[130:145]
	v_mfma_f32_32x32x16_bf16 v[234:249], v[218:221], v[230:233], v[234:249]
	ds_read2_b64 v[194:197], v251 offset0:104 offset1:106
	ds_read2_b64 v[218:221], v250 offset0:136 offset1:138
	s_nop 0
	v_cvt_pk_bf16_f32 v230, v74, v75
	v_cvt_pk_bf16_f32 v231, v76, v77
	v_cvt_pk_bf16_f32 v232, v78, v79
	v_cvt_pk_bf16_f32 v233, v80, v81
	s_waitcnt lgkmcnt(2)
	s_nop 1
	v_mfma_f32_32x32x16_bf16 v[130:145], v[222:225], v[230:233], v[130:145]
	v_mfma_f32_32x32x16_bf16 v[234:249], v[226:229], v[230:233], v[234:249]
	ds_read2_b64 v[222:225], v251 offset0:108 offset1:110
	ds_read2_b64 v[226:229], v250 offset0:140 offset1:142
	s_nop 0
	v_cvt_pk_bf16_f32 v230, v82, v83
	v_cvt_pk_bf16_f32 v231, v84, v85
	v_cvt_pk_bf16_f32 v232, v86, v87
	v_cvt_pk_bf16_f32 v233, v88, v89
	s_waitcnt lgkmcnt(2)
	s_nop 1
	v_mfma_f32_32x32x16_bf16 v[130:145], v[194:197], v[230:233], v[130:145]
	v_mfma_f32_32x32x16_bf16 v[234:249], v[218:221], v[230:233], v[234:249]
	ds_read2_b64 v[194:197], v251 offset0:112 offset1:114
	ds_read2_b64 v[218:221], v250 offset0:144 offset1:146
	s_nop 0
	v_cvt_pk_bf16_f32 v230, v90, v91
	v_cvt_pk_bf16_f32 v231, v92, v93
	v_cvt_pk_bf16_f32 v232, v94, v95
	v_cvt_pk_bf16_f32 v233, v96, v97
	s_waitcnt lgkmcnt(2)
	s_nop 1
	v_mfma_f32_32x32x16_bf16 v[130:145], v[222:225], v[230:233], v[130:145]
	v_mfma_f32_32x32x16_bf16 v[234:249], v[226:229], v[230:233], v[234:249]
	ds_read2_b64 v[222:225], v251 offset0:116 offset1:118
	ds_read2_b64 v[226:229], v250 offset0:148 offset1:150
	s_nop 0
	v_cvt_pk_bf16_f32 v230, v98, v99
	v_cvt_pk_bf16_f32 v231, v100, v101
	v_cvt_pk_bf16_f32 v232, v102, v103
	v_cvt_pk_bf16_f32 v233, v104, v105
	s_waitcnt lgkmcnt(2)
	s_nop 1
	v_mfma_f32_32x32x16_bf16 v[130:145], v[194:197], v[230:233], v[130:145]
	v_mfma_f32_32x32x16_bf16 v[234:249], v[218:221], v[230:233], v[234:249]
	ds_read2_b64 v[194:197], v251 offset0:120 offset1:122
	ds_read2_b64 v[218:221], v250 offset0:152 offset1:154
	s_nop 0
	v_cvt_pk_bf16_f32 v230, v106, v107
	v_cvt_pk_bf16_f32 v231, v108, v109
	v_cvt_pk_bf16_f32 v232, v110, v111
	v_cvt_pk_bf16_f32 v233, v112, v113
	s_waitcnt lgkmcnt(2)
	s_nop 1
	v_mfma_f32_32x32x16_bf16 v[130:145], v[222:225], v[230:233], v[130:145]
	v_mfma_f32_32x32x16_bf16 v[234:249], v[226:229], v[230:233], v[234:249]
	ds_read2_b64 v[222:225], v251 offset0:124 offset1:126
	ds_read2_b64 v[226:229], v250 offset0:156 offset1:158
	s_nop 0
	v_cvt_pk_bf16_f32 v230, v114, v115
	v_cvt_pk_bf16_f32 v231, v116, v117
	v_cvt_pk_bf16_f32 v232, v118, v119
	v_cvt_pk_bf16_f32 v233, v120, v121
	s_waitcnt lgkmcnt(2)
	s_nop 1
	v_mfma_f32_32x32x16_bf16 v[130:145], v[194:197], v[230:233], v[130:145]
	v_mfma_f32_32x32x16_bf16 v[234:249], v[218:221], v[230:233], v[234:249]
	s_nop 0
	v_cvt_pk_bf16_f32 v230, v122, v123
	v_cvt_pk_bf16_f32 v231, v124, v125
	v_cvt_pk_bf16_f32 v232, v126, v127
	v_cvt_pk_bf16_f32 v233, v128, v129
	s_waitcnt lgkmcnt(0)
	s_nop 1
	v_mfma_f32_32x32x16_bf16 v[130:145], v[222:225], v[230:233], v[130:145]
	v_mfma_f32_32x32x16_bf16 v[234:249], v[226:229], v[230:233], v[234:249]
	s_mov_b32 s100, 0xaaaaaaaa
	s_mov_b32 s101, 0xaaaaaaaa
	v_and_b32_e32 v220, 1, v189
	v_mul_u32_u24_e32 v220, 0xffe, v220
	v_mov_b32_e32 v221, 0
	v_lshl_add_u64 v[218:219], v[170:171], 0, v[172:173]
	v_lshl_add_u64 v[218:219], v[218:219], 0, v[220:221]
	s_mov_b32 s7, 0
	s_nop 7
	v_fmamk_f32 v222, v192, 0x42800000, v153
	v_fmamk_f32 v223, v192, 0x42820000, v153
	v_exp_f32_e32 v222, v222
	v_exp_f32_e32 v223, v223
	s_nop 0
	v_mul_f32_e32 v222, v222, v130
	v_mul_f32_e32 v223, v223, v131
	s_nop 1
	v_mov_b32_dpp v224, v222 quad_perm:[1,0,3,2] row_mask:0xf bank_mask:0xf
	v_mov_b32_dpp v225, v223 quad_perm:[1,0,3,2] row_mask:0xf bank_mask:0xf
	v_cndmask_b32_e64 v226, v222, v225, s[100:101]
	v_cndmask_b32_e64 v227, v224, v223, s[100:101]
	v_cvt_pk_bf16_f32 v226, v226, v227
	s_mov_b32 s6, 0x40000
	v_lshl_add_u64 v[228:229], v[218:219], 0, s[6:7]
	global_store_dword v[228:229], v226, off
	v_fmamk_f32 v222, v192, 0x42840000, v153
	v_fmamk_f32 v223, v192, 0x42860000, v153
	v_exp_f32_e32 v222, v222
	v_exp_f32_e32 v223, v223
	s_nop 0
	v_mul_f32_e32 v222, v222, v132
	v_mul_f32_e32 v223, v223, v133
	s_nop 1
	v_mov_b32_dpp v224, v222 quad_perm:[1,0,3,2] row_mask:0xf bank_mask:0xf
	v_mov_b32_dpp v225, v223 quad_perm:[1,0,3,2] row_mask:0xf bank_mask:0xf
	v_cndmask_b32_e64 v226, v222, v225, s[100:101]
	v_cndmask_b32_e64 v227, v224, v223, s[100:101]
	v_cvt_pk_bf16_f32 v226, v226, v227
	s_mov_b32 s6, 0x42000
	v_lshl_add_u64 v[228:229], v[218:219], 0, s[6:7]
	global_store_dword v[228:229], v226, off
	v_fmamk_f32 v222, v192, 0x42900000, v153
	v_fmamk_f32 v223, v192, 0x42920000, v153
	v_exp_f32_e32 v222, v222
	v_exp_f32_e32 v223, v223
	s_nop 0
	v_mul_f32_e32 v222, v222, v134
	v_mul_f32_e32 v223, v223, v135
	s_nop 1
	v_mov_b32_dpp v224, v222 quad_perm:[1,0,3,2] row_mask:0xf bank_mask:0xf
	v_mov_b32_dpp v225, v223 quad_perm:[1,0,3,2] row_mask:0xf bank_mask:0xf
	v_cndmask_b32_e64 v226, v222, v225, s[100:101]
	v_cndmask_b32_e64 v227, v224, v223, s[100:101]
	v_cvt_pk_bf16_f32 v226, v226, v227
	s_mov_b32 s6, 0x48000
	v_lshl_add_u64 v[228:229], v[218:219], 0, s[6:7]
	global_store_dword v[228:229], v226, off
	v_fmamk_f32 v222, v192, 0x42940000, v153
	v_fmamk_f32 v223, v192, 0x42960000, v153
	v_exp_f32_e32 v222, v222
	v_exp_f32_e32 v223, v223
	s_nop 0
	v_mul_f32_e32 v222, v222, v136
	v_mul_f32_e32 v223, v223, v137
	s_nop 1
	v_mov_b32_dpp v224, v222 quad_perm:[1,0,3,2] row_mask:0xf bank_mask:0xf
	v_mov_b32_dpp v225, v223 quad_perm:[1,0,3,2] row_mask:0xf bank_mask:0xf
	v_cndmask_b32_e64 v226, v222, v225, s[100:101]
	v_cndmask_b32_e64 v227, v224, v223, s[100:101]
	v_cvt_pk_bf16_f32 v226, v226, v227
	s_mov_b32 s6, 0x4a000
	v_lshl_add_u64 v[228:229], v[218:219], 0, s[6:7]
	global_store_dword v[228:229], v226, off
	v_fmamk_f32 v222, v192, 0x42a00000, v153
	v_fmamk_f32 v223, v192, 0x42a20000, v153
	v_exp_f32_e32 v222, v222
	v_exp_f32_e32 v223, v223
	s_nop 0
	v_mul_f32_e32 v222, v222, v138
	v_mul_f32_e32 v223, v223, v139
	s_nop 1
	v_mov_b32_dpp v224, v222 quad_perm:[1,0,3,2] row_mask:0xf bank_mask:0xf
	v_mov_b32_dpp v225, v223 quad_perm:[1,0,3,2] row_mask:0xf bank_mask:0xf
	v_cndmask_b32_e64 v226, v222, v225, s[100:101]
	v_cndmask_b32_e64 v227, v224, v223, s[100:101]
	v_cvt_pk_bf16_f32 v226, v226, v227
	s_mov_b32 s6, 0x50000
	v_lshl_add_u64 v[228:229], v[218:219], 0, s[6:7]
	global_store_dword v[228:229], v226, off
	v_fmamk_f32 v222, v192, 0x42a40000, v153
	v_fmamk_f32 v223, v192, 0x42a60000, v153
	v_exp_f32_e32 v222, v222
	v_exp_f32_e32 v223, v223
	s_nop 0
	v_mul_f32_e32 v222, v222, v140
	v_mul_f32_e32 v223, v223, v141
	s_nop 1
	v_mov_b32_dpp v224, v222 quad_perm:[1,0,3,2] row_mask:0xf bank_mask:0xf
	v_mov_b32_dpp v225, v223 quad_perm:[1,0,3,2] row_mask:0xf bank_mask:0xf
	v_cndmask_b32_e64 v226, v222, v225, s[100:101]
	v_cndmask_b32_e64 v227, v224, v223, s[100:101]
	v_cvt_pk_bf16_f32 v226, v226, v227
	s_mov_b32 s6, 0x52000
	v_lshl_add_u64 v[228:229], v[218:219], 0, s[6:7]
	global_store_dword v[228:229], v226, off
	v_fmamk_f32 v222, v192, 0x42b00000, v153
	v_fmamk_f32 v223, v192, 0x42b20000, v153
	v_exp_f32_e32 v222, v222
	v_exp_f32_e32 v223, v223
	s_nop 0
	v_mul_f32_e32 v222, v222, v142
	v_mul_f32_e32 v223, v223, v143
	s_nop 1
	v_mov_b32_dpp v224, v222 quad_perm:[1,0,3,2] row_mask:0xf bank_mask:0xf
	v_mov_b32_dpp v225, v223 quad_perm:[1,0,3,2] row_mask:0xf bank_mask:0xf
	v_cndmask_b32_e64 v226, v222, v225, s[100:101]
	v_cndmask_b32_e64 v227, v224, v223, s[100:101]
	v_cvt_pk_bf16_f32 v226, v226, v227
	s_mov_b32 s6, 0x58000
	v_lshl_add_u64 v[228:229], v[218:219], 0, s[6:7]
	global_store_dword v[228:229], v226, off
	v_fmamk_f32 v222, v192, 0x42b40000, v153
	v_fmamk_f32 v223, v192, 0x42b60000, v153
	v_exp_f32_e32 v222, v222
	v_exp_f32_e32 v223, v223
	s_nop 0
	v_mul_f32_e32 v222, v222, v144
	v_mul_f32_e32 v223, v223, v145
	s_nop 1
	v_mov_b32_dpp v224, v222 quad_perm:[1,0,3,2] row_mask:0xf bank_mask:0xf
	v_mov_b32_dpp v225, v223 quad_perm:[1,0,3,2] row_mask:0xf bank_mask:0xf
	v_cndmask_b32_e64 v226, v222, v225, s[100:101]
	v_cndmask_b32_e64 v227, v224, v223, s[100:101]
	v_cvt_pk_bf16_f32 v226, v226, v227
	s_mov_b32 s6, 0x5a000
	v_lshl_add_u64 v[228:229], v[218:219], 0, s[6:7]
	global_store_dword v[228:229], v226, off
	v_mov_b32_e32 v130, v234
	v_mov_b32_e32 v131, v235
	v_mov_b32_e32 v132, v236
	v_mov_b32_e32 v133, v237
	v_mov_b32_e32 v134, v238
	v_mov_b32_e32 v135, v239
	v_mov_b32_e32 v136, v240
	v_mov_b32_e32 v137, v241
	v_mov_b32_e32 v138, v242
	v_mov_b32_e32 v139, v243
	v_mov_b32_e32 v140, v244
	v_mov_b32_e32 v141, v245
	v_mov_b32_e32 v142, v246
	v_mov_b32_e32 v143, v247
	v_mov_b32_e32 v144, v248
	v_mov_b32_e32 v145, v249
	s_mov_b32 s100, 0xaaaaaaaa
	s_mov_b32 s101, 0xaaaaaaaa
	v_and_b32_e32 v220, 1, v189
	v_mul_u32_u24_e32 v220, 0xffe, v220
	v_mov_b32_e32 v221, 0
	v_lshl_add_u64 v[218:219], v[170:171], 0, v[172:173]
	v_lshl_add_u64 v[218:219], v[218:219], 0, v[220:221]
	s_mov_b32 s7, 0
	s_nop 7
	v_fmamk_f32 v222, v192, 0x42c00000, v153
	v_fmamk_f32 v223, v192, 0x42c20000, v153
	v_exp_f32_e32 v222, v222
	v_exp_f32_e32 v223, v223
	s_nop 0
	v_mul_f32_e32 v222, v222, v130
	v_mul_f32_e32 v223, v223, v131
	s_nop 1
	v_mov_b32_dpp v224, v222 quad_perm:[1,0,3,2] row_mask:0xf bank_mask:0xf
	v_mov_b32_dpp v225, v223 quad_perm:[1,0,3,2] row_mask:0xf bank_mask:0xf
	v_cndmask_b32_e64 v226, v222, v225, s[100:101]
	v_cndmask_b32_e64 v227, v224, v223, s[100:101]
	v_cvt_pk_bf16_f32 v226, v226, v227
	s_mov_b32 s6, 0x60000
	v_lshl_add_u64 v[228:229], v[218:219], 0, s[6:7]
	global_store_dword v[228:229], v226, off
	v_fmamk_f32 v222, v192, 0x42c40000, v153
	v_fmamk_f32 v223, v192, 0x42c60000, v153
	v_exp_f32_e32 v222, v222
	v_exp_f32_e32 v223, v223
	s_nop 0
	v_mul_f32_e32 v222, v222, v132
	v_mul_f32_e32 v223, v223, v133
	s_nop 1
	v_mov_b32_dpp v224, v222 quad_perm:[1,0,3,2] row_mask:0xf bank_mask:0xf
	v_mov_b32_dpp v225, v223 quad_perm:[1,0,3,2] row_mask:0xf bank_mask:0xf
	v_cndmask_b32_e64 v226, v222, v225, s[100:101]
	v_cndmask_b32_e64 v227, v224, v223, s[100:101]
	v_cvt_pk_bf16_f32 v226, v226, v227
	s_mov_b32 s6, 0x62000
	v_lshl_add_u64 v[228:229], v[218:219], 0, s[6:7]
	global_store_dword v[228:229], v226, off
	v_fmamk_f32 v222, v192, 0x42d00000, v153
	v_fmamk_f32 v223, v192, 0x42d20000, v153
	v_exp_f32_e32 v222, v222
	v_exp_f32_e32 v223, v223
	s_nop 0
	v_mul_f32_e32 v222, v222, v134
	v_mul_f32_e32 v223, v223, v135
	s_nop 1
	v_mov_b32_dpp v224, v222 quad_perm:[1,0,3,2] row_mask:0xf bank_mask:0xf
	v_mov_b32_dpp v225, v223 quad_perm:[1,0,3,2] row_mask:0xf bank_mask:0xf
	v_cndmask_b32_e64 v226, v222, v225, s[100:101]
	v_cndmask_b32_e64 v227, v224, v223, s[100:101]
	v_cvt_pk_bf16_f32 v226, v226, v227
	s_mov_b32 s6, 0x68000
	v_lshl_add_u64 v[228:229], v[218:219], 0, s[6:7]
	global_store_dword v[228:229], v226, off
	v_fmamk_f32 v222, v192, 0x42d40000, v153
	v_fmamk_f32 v223, v192, 0x42d60000, v153
	v_exp_f32_e32 v222, v222
	v_exp_f32_e32 v223, v223
	s_nop 0
	v_mul_f32_e32 v222, v222, v136
	v_mul_f32_e32 v223, v223, v137
	s_nop 1
	v_mov_b32_dpp v224, v222 quad_perm:[1,0,3,2] row_mask:0xf bank_mask:0xf
	v_mov_b32_dpp v225, v223 quad_perm:[1,0,3,2] row_mask:0xf bank_mask:0xf
	v_cndmask_b32_e64 v226, v222, v225, s[100:101]
	v_cndmask_b32_e64 v227, v224, v223, s[100:101]
	v_cvt_pk_bf16_f32 v226, v226, v227
	s_mov_b32 s6, 0x6a000
	v_lshl_add_u64 v[228:229], v[218:219], 0, s[6:7]
	global_store_dword v[228:229], v226, off
	v_fmamk_f32 v222, v192, 0x42e00000, v153
	v_fmamk_f32 v223, v192, 0x42e20000, v153
	v_exp_f32_e32 v222, v222
	v_exp_f32_e32 v223, v223
	s_nop 0
	v_mul_f32_e32 v222, v222, v138
	v_mul_f32_e32 v223, v223, v139
	s_nop 1
	v_mov_b32_dpp v224, v222 quad_perm:[1,0,3,2] row_mask:0xf bank_mask:0xf
	v_mov_b32_dpp v225, v223 quad_perm:[1,0,3,2] row_mask:0xf bank_mask:0xf
	v_cndmask_b32_e64 v226, v222, v225, s[100:101]
	v_cndmask_b32_e64 v227, v224, v223, s[100:101]
	v_cvt_pk_bf16_f32 v226, v226, v227
	s_mov_b32 s6, 0x70000
	v_lshl_add_u64 v[228:229], v[218:219], 0, s[6:7]
	global_store_dword v[228:229], v226, off
	v_fmamk_f32 v222, v192, 0x42e40000, v153
	v_fmamk_f32 v223, v192, 0x42e60000, v153
	v_exp_f32_e32 v222, v222
	v_exp_f32_e32 v223, v223
	s_nop 0
	v_mul_f32_e32 v222, v222, v140
	v_mul_f32_e32 v223, v223, v141
	s_nop 1
	v_mov_b32_dpp v224, v222 quad_perm:[1,0,3,2] row_mask:0xf bank_mask:0xf
	v_mov_b32_dpp v225, v223 quad_perm:[1,0,3,2] row_mask:0xf bank_mask:0xf
	v_cndmask_b32_e64 v226, v222, v225, s[100:101]
	v_cndmask_b32_e64 v227, v224, v223, s[100:101]
	v_cvt_pk_bf16_f32 v226, v226, v227
	s_mov_b32 s6, 0x72000
	v_lshl_add_u64 v[228:229], v[218:219], 0, s[6:7]
	global_store_dword v[228:229], v226, off
	v_fmamk_f32 v222, v192, 0x42f00000, v153
	v_fmamk_f32 v223, v192, 0x42f20000, v153
	v_exp_f32_e32 v222, v222
	v_exp_f32_e32 v223, v223
	s_nop 0
	v_mul_f32_e32 v222, v222, v142
	v_mul_f32_e32 v223, v223, v143
	s_nop 1
	v_mov_b32_dpp v224, v222 quad_perm:[1,0,3,2] row_mask:0xf bank_mask:0xf
	v_mov_b32_dpp v225, v223 quad_perm:[1,0,3,2] row_mask:0xf bank_mask:0xf
	v_cndmask_b32_e64 v226, v222, v225, s[100:101]
	v_cndmask_b32_e64 v227, v224, v223, s[100:101]
	v_cvt_pk_bf16_f32 v226, v226, v227
	s_mov_b32 s6, 0x78000
	v_lshl_add_u64 v[228:229], v[218:219], 0, s[6:7]
	global_store_dword v[228:229], v226, off
	v_fmamk_f32 v222, v192, 0x42f40000, v153
	v_fmamk_f32 v223, v192, 0x42f60000, v153
	v_exp_f32_e32 v222, v222
	v_exp_f32_e32 v223, v223
	s_nop 0
	v_mul_f32_e32 v222, v222, v144
	v_mul_f32_e32 v223, v223, v145
	s_nop 1
	v_mov_b32_dpp v224, v222 quad_perm:[1,0,3,2] row_mask:0xf bank_mask:0xf
	v_mov_b32_dpp v225, v223 quad_perm:[1,0,3,2] row_mask:0xf bank_mask:0xf
	v_cndmask_b32_e64 v226, v222, v225, s[100:101]
	v_cndmask_b32_e64 v227, v224, v223, s[100:101]
	v_cvt_pk_bf16_f32 v226, v226, v227
	s_mov_b32 s6, 0x7a000
	v_lshl_add_u64 v[228:229], v[218:219], 0, s[6:7]
	global_store_dword v[228:229], v226, off
	v_mov_b32_e32 v153, v189
	s_waitcnt vmcnt(63) expcnt(7) lgkmcnt(15)
	s_barrier
	v_lshl_add_u64 v[132:133], s[64:65], 0, v[164:165]
	v_lshlrev_b64 v[130:131], 1, v[168:169]
	v_lshlrev_b64 v[226:227], 14, v[166:167]
	v_lshl_add_u64 v[226:227], s[64:65], 0, v[226:227]
	v_lshl_add_u64 v[226:227], v[226:227], 0, v[130:131]
	v_mov_b32_e32 v228, v152
	v_mov_b32_e32 v229, v1
	v_lshl_add_u64 v[226:227], v[226:227], 0, v[228:229]
	s_mov_b64 s[6:7], 0xf640000
	v_lshl_add_u64 v[226:227], v[226:227], 0, s[6:7]
	global_load_dwordx4 v[234:237], v[226:227], off
	global_load_dwordx4 v[238:241], v[226:227], off offset:32
	global_load_dwordx4 v[242:245], v[226:227], off offset:64
	global_load_dwordx4 v[246:249], v[226:227], off offset:96
	v_lshl_add_u64 v[132:133], v[132:133], 0, v[130:131]
	v_lshlrev_b32_e32 v134, 4, v153
	v_and_b32_e32 v144, 0xf0, v134
	v_mov_b32_e32 v145, v1
	v_lshlrev_b32_e32 v134, 10, v153
	v_lshl_add_u64 v[132:133], v[132:133], 0, v[144:145]
	v_and_b32_e32 v134, 0x3c000, v134
	v_mov_b32_e32 v135, v1
	v_lshl_add_u64 v[172:173], v[132:133], 0, v[134:135]
	s_mov_b32 s6, 0xe640000
	v_add_co_u32_e64 v132, s[6:7], s6, v172
	v_bfe_u32 v145, v153, 4, 4
	s_nop 0
	v_addc_co_u32_e64 v133, s[6:7], 0, v173, s[6:7]
	s_mov_b32 s6, 0xe680000
	s_nop 0
	v_add_co_u32_e64 v136, s[6:7], s6, v172
	global_load_dwordx4 v[132:135], v[132:133], off
	s_nop 0
	v_addc_co_u32_e64 v137, s[6:7], 0, v173, s[6:7]
	s_mov_b32 s6, 0xe6c0000
	s_nop 0
	v_add_co_u32_e64 v140, s[6:7], s6, v172
	global_load_dwordx4 v[136:139], v[136:137], off
	s_nop 0
	v_addc_co_u32_e64 v141, s[6:7], 0, v173, s[6:7]
	s_mov_b32 s6, 0xe700000
	s_nop 0
	v_add_co_u32_e64 v168, s[6:7], s6, v172
	global_load_dwordx4 v[140:143], v[140:141], off
	s_nop 0
	v_addc_co_u32_e64 v169, s[6:7], 0, v173, s[6:7]
	s_mov_b32 s6, 0xe740000
	s_nop 0
	v_add_co_u32_e64 v192, s[6:7], s6, v172
	global_load_dwordx4 v[168:171], v[168:169], off
	s_nop 0
	v_addc_co_u32_e64 v193, s[6:7], 0, v173, s[6:7]
	s_mov_b32 s6, 0xe780000
	s_nop 0
	v_add_co_u32_e64 v196, s[6:7], s6, v172
	global_load_dwordx4 v[192:195], v[192:193], off
	s_nop 0
	v_addc_co_u32_e64 v197, s[6:7], 0, v173, s[6:7]
	s_mov_b32 s6, 0xe7c0000
	s_nop 0
	v_add_co_u32_e64 v208, s[6:7], s6, v172
	global_load_dwordx4 v[196:199], v[196:197], off
	s_nop 0
	v_addc_co_u32_e64 v209, s[6:7], 0, v173, s[6:7]
	s_mov_b32 s6, 0xe800000
	global_load_dwordx4 v[218:221], v[208:209], off
	v_add_co_u32_e64 v208, s[6:7], s6, v172
	v_mul_u32_u24_e32 v145, 0x108, v145
	s_nop 0
	v_addc_co_u32_e64 v209, s[6:7], 0, v173, s[6:7]
	global_load_dwordx4 v[222:225], v[208:209], off
	v_add3_u32 v153, v149, v144, v145
	s_waitcnt vmcnt(7)
	ds_write2_b64 v153, v[132:133], v[134:135] offset1:1
	v_add_u32_e32 v132, 0x1080, v153
	s_waitcnt vmcnt(6)
	ds_write2_b64 v132, v[136:137], v[138:139] offset1:1
	v_add_u32_e32 v132, 0x2100, v153
	s_waitcnt vmcnt(5)
	ds_write2_b64 v132, v[140:141], v[142:143] offset1:1
	v_add_u32_e32 v132, 0x3180, v153
	s_waitcnt vmcnt(4)
	ds_write2_b64 v132, v[168:169], v[170:171] offset1:1
	v_add_u32_e32 v132, 0x4200, v153
	s_waitcnt vmcnt(3)
	ds_write2_b64 v132, v[192:193], v[194:195] offset1:1
	v_add_u32_e32 v132, 0x5280, v153
	s_waitcnt vmcnt(2)
	ds_write2_b64 v132, v[196:197], v[198:199] offset1:1
	v_add_u32_e32 v132, 0x6300, v153
	s_waitcnt vmcnt(1)
	ds_write2_b64 v132, v[218:219], v[220:221] offset1:1
	v_add_u32_e32 v132, 0x7380, v153
	s_waitcnt vmcnt(0)
	ds_write2_b64 v132, v[222:223], v[224:225] offset1:1
	s_mov_b32 s6, 0xe840000
	v_add_co_u32_e64 v132, s[6:7], s6, v172
	s_nop 1
	v_addc_co_u32_e64 v133, s[6:7], 0, v173, s[6:7]
	s_mov_b32 s6, 0xe880000
	s_nop 0
	v_add_co_u32_e64 v136, s[6:7], s6, v172
	global_load_dwordx4 v[132:135], v[132:133], off
	s_nop 0
	v_addc_co_u32_e64 v137, s[6:7], 0, v173, s[6:7]
	s_mov_b32 s6, 0xe8c0000
	s_nop 0
	v_add_co_u32_e64 v140, s[6:7], s6, v172
	global_load_dwordx4 v[136:139], v[136:137], off
	s_nop 0
	v_addc_co_u32_e64 v141, s[6:7], 0, v173, s[6:7]
	s_mov_b32 s6, 0xe900000
	s_nop 0
	v_add_co_u32_e64 v144, s[6:7], s6, v172
	global_load_dwordx4 v[140:143], v[140:141], off
	s_nop 0
	v_addc_co_u32_e64 v145, s[6:7], 0, v173, s[6:7]
	s_mov_b32 s6, 0xe940000
	global_load_dwordx4 v[168:171], v[144:145], off
	v_add_co_u32_e64 v144, s[6:7], s6, v172
	s_nop 1
	v_addc_co_u32_e64 v145, s[6:7], 0, v173, s[6:7]
	s_mov_b32 s6, 0xe980000
	global_load_dwordx4 v[192:195], v[144:145], off
	v_add_co_u32_e64 v144, s[6:7], s6, v172
	s_nop 1
	v_addc_co_u32_e64 v145, s[6:7], 0, v173, s[6:7]
	s_mov_b32 s6, 0xe9c0000
	global_load_dwordx4 v[196:199], v[144:145], off
	v_add_co_u32_e64 v144, s[6:7], s6, v172
	s_nop 1
	v_addc_co_u32_e64 v145, s[6:7], 0, v173, s[6:7]
	s_mov_b32 s6, 0xea00000
	global_load_dwordx4 v[218:221], v[144:145], off
	v_add_co_u32_e64 v144, s[6:7], s6, v172
	s_nop 1
	v_addc_co_u32_e64 v145, s[6:7], 0, v173, s[6:7]
	global_load_dwordx4 v[222:225], v[144:145], off
	v_add_u32_e32 v144, 0x8400, v153
	s_waitcnt vmcnt(7)
	ds_write2_b64 v144, v[132:133], v[134:135] offset1:1
	v_add_u32_e32 v132, 0x9480, v153
	s_waitcnt vmcnt(6)
	ds_write2_b64 v132, v[136:137], v[138:139] offset1:1
	v_add_u32_e32 v132, 0xa500, v153
	s_waitcnt vmcnt(5)
	ds_write2_b64 v132, v[140:141], v[142:143] offset1:1
	v_add_u32_e32 v132, 0xb580, v153
	s_waitcnt vmcnt(4)
	ds_write2_b64 v132, v[168:169], v[170:171] offset1:1
	v_add_u32_e32 v132, 0xc600, v153
	s_waitcnt vmcnt(3)
	ds_write2_b64 v132, v[192:193], v[194:195] offset1:1
	v_add_u32_e32 v132, 0xd680, v153
	s_waitcnt vmcnt(2)
	ds_write2_b64 v132, v[196:197], v[198:199] offset1:1
	v_add_u32_e32 v132, 0xe700, v153
	s_waitcnt vmcnt(1)
	ds_write2_b64 v132, v[218:219], v[220:221] offset1:1
	v_add_u32_e32 v132, 0xf780, v153
	s_waitcnt vmcnt(0)
	ds_write2_b64 v132, v[222:223], v[224:225] offset1:1
	s_waitcnt lgkmcnt(0)
	s_barrier
	v_lshlrev_b64 v[132:133], 14, v[166:167]
	v_lshl_add_u64 v[132:133], s[64:65], 0, v[132:133]
	v_lshl_add_u64 v[130:131], v[132:133], 0, v[130:131]
	v_mov_b32_e32 v153, v1
	v_lshl_add_u64 v[134:135], v[130:131], 0, v[152:153]
	s_mov_b32 s6, 0xf640000
	v_add_co_u32_e64 v130, s[6:7], s6, v134
	v_mul_f32 v2, v2, v159
	v_mul_f32 v3, v3, v159
	v_mul_f32 v4, v4, v159
	v_mul_f32 v5, v5, v159
	s_nop 1
	v_addc_co_u32_e64 v131, s[6:7], 0, v135, s[6:7]
	v_mul_f32 v6, v6, v159
	v_mul_f32 v7, v7, v159
	v_mul_f32 v8, v8, v159
	v_mul_f32 v9, v9, v159
	v_mul_f32 v10, v10, v159
	v_mul_f32 v11, v11, v159
	v_mul_f32 v12, v12, v159
	v_mul_f32 v13, v13, v159
	v_mul_f32 v14, v14, v159
	v_mul_f32 v15, v15, v159
	v_mul_f32 v16, v16, v159
	v_mul_f32 v17, v17, v159
	v_mul_f32 v18, v18, v159
	v_mul_f32 v19, v19, v159
	v_mul_f32 v20, v20, v159
	v_mul_f32 v21, v21, v159
	v_mul_f32 v22, v22, v159
	v_mul_f32 v23, v23, v159
	v_mul_f32 v24, v24, v159
	v_mul_f32 v25, v25, v159
	v_mul_f32 v26, v26, v159
	v_mul_f32 v27, v27, v159
	v_mul_f32 v28, v28, v159
	v_mul_f32 v29, v29, v159
	v_mul_f32 v30, v30, v159
	v_mul_f32 v31, v31, v159
	v_mul_f32 v32, v32, v159
	v_mul_f32 v33, v33, v159
	v_mul_f32 v34, v34, v159
	v_mul_f32 v35, v35, v159
	v_mul_f32 v36, v36, v159
	v_mul_f32 v37, v37, v159
	v_mul_f32 v38, v38, v159
	v_mul_f32 v39, v39, v159
	v_mul_f32 v40, v40, v159
	v_mul_f32 v41, v41, v159
	v_mul_f32 v42, v42, v159
	v_mul_f32 v43, v43, v159
	v_mul_f32 v44, v44, v159
	v_mul_f32 v45, v45, v159
	v_mul_f32 v46, v46, v159
	v_mul_f32 v47, v47, v159
	v_mul_f32 v48, v48, v159
	v_mul_f32 v49, v49, v159
	v_mul_f32 v50, v50, v159
	v_mul_f32 v51, v51, v159
	v_mul_f32 v52, v52, v159
	v_mul_f32 v53, v53, v159
	v_mul_f32 v54, v54, v159
	v_mul_f32 v55, v55, v159
	v_mul_f32 v56, v56, v159
	v_mul_f32 v57, v57, v159
	v_mul_f32 v58, v58, v159
	v_mul_f32 v59, v59, v159
	v_mul_f32 v60, v60, v159
	v_mul_f32 v61, v61, v159
	v_mul_f32 v62, v62, v159
	v_mul_f32 v63, v63, v159
	v_mul_f32 v64, v64, v159
	v_mul_f32 v65, v65, v159
	v_mul_f32 v66, v66, v159
	v_mul_f32 v67, v67, v159
	v_mul_f32 v68, v68, v159
	v_mul_f32 v69, v69, v159
	v_mul_f32 v70, v70, v159
	v_mul_f32 v71, v71, v159
	v_mul_f32 v72, v72, v159
	v_mul_f32 v73, v73, v159
	v_mul_f32 v74, v74, v159
	v_mul_f32 v75, v75, v159
	v_mul_f32 v76, v76, v159
	v_mul_f32 v77, v77, v159
	v_mul_f32 v78, v78, v159
	v_mul_f32 v79, v79, v159
	v_mul_f32 v80, v80, v159
	v_mul_f32 v81, v81, v159
	v_mul_f32 v82, v82, v159
	v_mul_f32 v83, v83, v159
	v_mul_f32 v84, v84, v159
	v_mul_f32 v85, v85, v159
	v_mul_f32 v86, v86, v159
	v_mul_f32 v87, v87, v159
	v_mul_f32 v88, v88, v159
	v_mul_f32 v89, v89, v159
	v_mul_f32 v90, v90, v159
	v_mul_f32 v91, v91, v159
	v_mul_f32 v92, v92, v159
	v_mul_f32 v93, v93, v159
	v_mul_f32 v94, v94, v159
	v_mul_f32 v95, v95, v159
	v_mul_f32 v96, v96, v159
	v_mul_f32 v97, v97, v159
	v_mul_f32 v98, v98, v159
	v_mul_f32 v99, v99, v159
	v_mul_f32 v100, v100, v159
	v_mul_f32 v101, v101, v159
	v_mul_f32 v102, v102, v159
	v_mul_f32 v103, v103, v159
	v_mul_f32 v104, v104, v159
	v_mul_f32 v105, v105, v159
	v_mul_f32 v106, v106, v159
	v_mul_f32 v107, v107, v159
	v_mul_f32 v108, v108, v159
	v_mul_f32 v109, v109, v159
	v_mul_f32 v110, v110, v159
	v_mul_f32 v111, v111, v159
	v_mul_f32 v112, v112, v159
	v_mul_f32 v113, v113, v159
	v_mul_f32 v114, v114, v159
	v_mul_f32 v115, v115, v159
	v_mul_f32 v116, v116, v159
	v_mul_f32 v117, v117, v159
	v_mul_f32 v118, v118, v159
	v_mul_f32 v119, v119, v159
	v_mul_f32 v120, v120, v159
	v_mul_f32 v121, v121, v159
	v_mul_f32 v122, v122, v159
	v_mul_f32 v123, v123, v159
	v_mul_f32 v124, v124, v159
	v_mul_f32 v125, v125, v159
	v_mul_f32 v126, v126, v159
	v_mul_f32 v127, v127, v159
	v_mul_f32 v128, v128, v159
	v_mul_f32 v129, v129, v159
	s_mov_b64 s[6:7], 0xf640000
	v_lshl_add_u64 v[142:143], v[134:135], 0, s[6:7]
	v_mov_b32_e32 v130, v234
	v_mov_b32_e32 v131, v235
	v_mov_b32_e32 v132, v236
	v_mov_b32_e32 v133, v237
	v_mov_b32_e32 v134, v238
	v_mov_b32_e32 v135, v239
	v_mov_b32_e32 v136, v240
	v_mov_b32_e32 v137, v241
	v_mov_b32_e32 v138, v242
	v_mov_b32_e32 v139, v243
	v_mov_b32_e32 v140, v244
	v_mov_b32_e32 v141, v245
	v_mov_b32_e32 v166, v246
	v_mov_b32_e32 v167, v247
	v_mov_b32_e32 v168, v248
	v_mov_b32_e32 v169, v249
	global_load_dwordx4 v[234:237], v[142:143], off offset:128
	global_load_dwordx4 v[238:241], v[142:143], off offset:160
	global_load_dwordx4 v[242:245], v[142:143], off offset:192
	global_load_dwordx4 v[246:249], v[142:143], off offset:224
	v_fma_f32 v144, 0, v191, v190
	v_add_f32_e32 v145, v190, v191
	v_exp_f32_e32 v144, v144
	v_exp_f32_e32 v145, v145
	v_fmamk_f32 v153, v191, 0x42480000, v190
	s_waitcnt vmcnt(4)
	v_lshlrev_b32_e32 v170, 16, v130
	v_and_b32_e32 v171, 0xffff0000, v130
	v_fma_f32 v130, 2.0, v191, v190
	v_pk_mul_f32 v[144:145], v[144:145], v[170:171]
	v_exp_f32_e32 v170, v130
	v_fmamk_f32 v130, v191, 0x40400000, v190
	v_exp_f32_e32 v171, v130
	v_cvt_pk_bf16_f32 v130, v144, v145
	v_lshlrev_b32_e32 v144, 16, v131
	v_and_b32_e32 v145, 0xffff0000, v131
	v_fma_f32 v131, 4.0, v191, v190
	v_pk_mul_f32 v[144:145], v[170:171], v[144:145]
	v_exp_f32_e32 v170, v131
	v_fmamk_f32 v131, v191, 0x40a00000, v190
	v_exp_f32_e32 v171, v131
	v_cvt_pk_bf16_f32 v131, v144, v145
	v_lshlrev_b32_e32 v144, 16, v132
	v_and_b32_e32 v145, 0xffff0000, v132
	v_fmamk_f32 v132, v191, 0x40c00000, v190
	v_pk_mul_f32 v[144:145], v[170:171], v[144:145]
	v_exp_f32_e32 v170, v132
	v_fmamk_f32 v132, v191, 0x40e00000, v190
	v_exp_f32_e32 v171, v132
	v_cvt_pk_bf16_f32 v132, v144, v145
	v_lshlrev_b32_e32 v144, 16, v133
	v_and_b32_e32 v145, 0xffff0000, v133
	v_fmamk_f32 v133, v191, 0x41800000, v190
	v_pk_mul_f32 v[144:145], v[170:171], v[144:145]
	v_exp_f32_e32 v170, v133
	v_fmamk_f32 v133, v191, 0x41880000, v190
	v_exp_f32_e32 v171, v133
	v_cvt_pk_bf16_f32 v133, v144, v145
	s_waitcnt vmcnt(4)
	v_lshlrev_b32_e32 v144, 16, v134
	v_and_b32_e32 v145, 0xffff0000, v134
	v_fmamk_f32 v134, v191, 0x41900000, v190
	v_pk_mul_f32 v[144:145], v[170:171], v[144:145]
	v_exp_f32_e32 v170, v134
	v_fmamk_f32 v134, v191, 0x41980000, v190
	v_exp_f32_e32 v171, v134
	v_cvt_pk_bf16_f32 v134, v144, v145
	v_lshlrev_b32_e32 v144, 16, v135
	v_and_b32_e32 v145, 0xffff0000, v135
	v_fmamk_f32 v135, v191, 0x41a00000, v190
	v_pk_mul_f32 v[144:145], v[170:171], v[144:145]
	v_exp_f32_e32 v170, v135
	v_fmamk_f32 v135, v191, 0x41a80000, v190
	v_exp_f32_e32 v171, v135
	v_cvt_pk_bf16_f32 v135, v144, v145
	v_lshlrev_b32_e32 v144, 16, v136
	v_and_b32_e32 v145, 0xffff0000, v136
	v_fmamk_f32 v136, v191, 0x41b00000, v190
	v_pk_mul_f32 v[144:145], v[170:171], v[144:145]
	v_exp_f32_e32 v170, v136
	v_fmamk_f32 v136, v191, 0x41b80000, v190
	v_exp_f32_e32 v171, v136
	v_cvt_pk_bf16_f32 v136, v144, v145
	v_lshlrev_b32_e32 v144, 16, v137
	v_and_b32_e32 v145, 0xffff0000, v137
	v_fmamk_f32 v137, v191, 0x42000000, v190
	v_pk_mul_f32 v[144:145], v[170:171], v[144:145]
	v_exp_f32_e32 v170, v137
	v_fmamk_f32 v137, v191, 0x42040000, v190
	v_exp_f32_e32 v171, v137
	v_cvt_pk_bf16_f32 v137, v144, v145
	s_waitcnt vmcnt(4)
	v_lshlrev_b32_e32 v144, 16, v138
	v_and_b32_e32 v145, 0xffff0000, v138
	v_fmamk_f32 v138, v191, 0x42080000, v190
	v_pk_mul_f32 v[144:145], v[170:171], v[144:145]
	v_exp_f32_e32 v170, v138
	v_fmamk_f32 v138, v191, 0x420c0000, v190
	v_exp_f32_e32 v171, v138
	v_cvt_pk_bf16_f32 v138, v144, v145
	v_lshlrev_b32_e32 v144, 16, v139
	v_and_b32_e32 v145, 0xffff0000, v139
	v_fmamk_f32 v139, v191, 0x42100000, v190
	v_pk_mul_f32 v[144:145], v[170:171], v[144:145]
	v_exp_f32_e32 v170, v139
	v_fmamk_f32 v139, v191, 0x42140000, v190
	v_exp_f32_e32 v171, v139
	v_cvt_pk_bf16_f32 v139, v144, v145
	v_lshlrev_b32_e32 v144, 16, v140
	v_and_b32_e32 v145, 0xffff0000, v140
	v_fmamk_f32 v140, v191, 0x42180000, v190
	v_pk_mul_f32 v[144:145], v[170:171], v[144:145]
	v_exp_f32_e32 v170, v140
	v_fmamk_f32 v140, v191, 0x421c0000, v190
	v_exp_f32_e32 v171, v140
	v_cvt_pk_bf16_f32 v140, v144, v145
	v_lshlrev_b32_e32 v144, 16, v141
	v_and_b32_e32 v145, 0xffff0000, v141
	v_fmamk_f32 v141, v191, 0x42400000, v190
	v_pk_mul_f32 v[144:145], v[170:171], v[144:145]
	v_exp_f32_e32 v170, v141
	v_fmamk_f32 v141, v191, 0x42440000, v190
	v_exp_f32_e32 v171, v141
	v_cvt_pk_bf16_f32 v141, v144, v145
	s_waitcnt vmcnt(4)
	v_lshlrev_b32_e32 v144, 16, v166
	v_and_b32_e32 v145, 0xffff0000, v166
	v_pk_mul_f32 v[144:145], v[170:171], v[144:145]
	v_exp_f32_e32 v170, v153
	v_fmamk_f32 v153, v191, 0x424c0000, v190
	v_exp_f32_e32 v171, v153
	v_cvt_pk_bf16_f32 v166, v144, v145
	v_lshlrev_b32_e32 v144, 16, v167
	v_and_b32_e32 v145, 0xffff0000, v167
	v_fmamk_f32 v153, v191, 0x42500000, v190
	v_pk_mul_f32 v[144:145], v[170:171], v[144:145]
	v_exp_f32_e32 v170, v153
	v_fmamk_f32 v153, v191, 0x42540000, v190
	v_exp_f32_e32 v171, v153
	v_cvt_pk_bf16_f32 v167, v144, v145
	v_lshlrev_b32_e32 v144, 16, v168
	v_and_b32_e32 v145, 0xffff0000, v168
	v_fmamk_f32 v153, v191, 0x42580000, v190
	v_pk_mul_f32 v[144:145], v[170:171], v[144:145]
	v_exp_f32_e32 v170, v153
	v_fmamk_f32 v153, v191, 0x425c0000, v190
	v_exp_f32_e32 v171, v153
	v_cvt_pk_bf16_f32 v168, v144, v145
	v_lshlrev_b32_e32 v144, 16, v169
	v_and_b32_e32 v145, 0xffff0000, v169
	v_pk_mul_f32 v[144:145], v[170:171], v[144:145]
	s_nop 0
	v_cvt_pk_bf16_f32 v169, v144, v145
	ds_read2_b64 v[170:173], v179 offset1:1
	ds_read2_b64 v[192:195], v179 offset0:4 offset1:5
	ds_read2_b64 v[196:199], v179 offset0:8 offset1:9
	ds_read2_b64 v[218:221], v179 offset0:12 offset1:13
	s_waitcnt lgkmcnt(3)
	v_mfma_f32_32x32x16_bf16 v[2:17], v[170:173], v[130:133], v[2:17]
	v_add_u32_e32 v144, 0x2100, v179
	ds_read2_b64 v[170:173], v144 offset1:1
	s_waitcnt lgkmcnt(3)
	v_mfma_f32_32x32x16_bf16 v[2:17], v[192:195], v[134:137], v[2:17]
	v_add_u32_e32 v144, 0x2120, v179
	ds_read2_b64 v[192:195], v144 offset1:1
	s_waitcnt lgkmcnt(3)
	v_mfma_f32_32x32x16_bf16 v[2:17], v[196:199], v[138:141], v[2:17]
	v_add_u32_e32 v144, 0x2140, v179
	ds_read2_b64 v[196:199], v144 offset1:1
	s_waitcnt lgkmcnt(3)
	v_mfma_f32_32x32x16_bf16 v[2:17], v[218:221], v[166:169], v[2:17]
	v_add_u32_e32 v144, 0x2160, v179
	ds_read2_b64 v[218:221], v144 offset1:1
	s_waitcnt lgkmcnt(3)
	v_mfma_f32_32x32x16_bf16 v[18:33], v[170:173], v[130:133], v[18:33]
	v_add_u32_e32 v144, 0x4200, v179
	ds_read2_b64 v[170:173], v144 offset1:1
	s_waitcnt lgkmcnt(3)
	v_mfma_f32_32x32x16_bf16 v[18:33], v[192:195], v[134:137], v[18:33]
	v_add_u32_e32 v144, 0x4220, v179
	ds_read2_b64 v[192:195], v144 offset1:1
	s_waitcnt lgkmcnt(3)
	v_mfma_f32_32x32x16_bf16 v[18:33], v[196:199], v[138:141], v[18:33]
	v_add_u32_e32 v144, 0x4240, v179
	ds_read2_b64 v[196:199], v144 offset1:1
	s_waitcnt lgkmcnt(3)
	v_mfma_f32_32x32x16_bf16 v[18:33], v[218:221], v[166:169], v[18:33]
	v_add_u32_e32 v144, 0x4260, v179
	ds_read2_b64 v[218:221], v144 offset1:1
	s_waitcnt lgkmcnt(3)
	v_mfma_f32_32x32x16_bf16 v[34:49], v[170:173], v[130:133], v[34:49]
	v_add_u32_e32 v144, 0x6300, v179
	ds_read2_b64 v[170:173], v144 offset1:1
	s_waitcnt lgkmcnt(3)
	v_mfma_f32_32x32x16_bf16 v[34:49], v[192:195], v[134:137], v[34:49]
	v_add_u32_e32 v144, 0x6320, v179
	ds_read2_b64 v[192:195], v144 offset1:1
	s_waitcnt lgkmcnt(3)
	v_mfma_f32_32x32x16_bf16 v[34:49], v[196:199], v[138:141], v[34:49]
	v_add_u32_e32 v144, 0x6340, v179
	ds_read2_b64 v[196:199], v144 offset1:1
	s_waitcnt lgkmcnt(3)
	v_mfma_f32_32x32x16_bf16 v[34:49], v[218:221], v[166:169], v[34:49]
	v_add_u32_e32 v144, 0x6360, v179
	ds_read2_b64 v[218:221], v144 offset1:1
	s_waitcnt lgkmcnt(3)
	v_mfma_f32_32x32x16_bf16 v[50:65], v[170:173], v[130:133], v[50:65]
	v_add_u32_e32 v144, 0x8400, v179
	ds_read2_b64 v[170:173], v144 offset1:1
	s_waitcnt lgkmcnt(3)
	v_mfma_f32_32x32x16_bf16 v[50:65], v[192:195], v[134:137], v[50:65]
	v_add_u32_e32 v144, 0x8420, v179
	ds_read2_b64 v[192:195], v144 offset1:1
	s_waitcnt lgkmcnt(3)
	v_mfma_f32_32x32x16_bf16 v[50:65], v[196:199], v[138:141], v[50:65]
	v_add_u32_e32 v144, 0x8440, v179
	ds_read2_b64 v[196:199], v144 offset1:1
	s_waitcnt lgkmcnt(3)
	v_mfma_f32_32x32x16_bf16 v[50:65], v[218:221], v[166:169], v[50:65]
	v_add_u32_e32 v144, 0x8460, v179
	ds_read2_b64 v[218:221], v144 offset1:1
	s_waitcnt lgkmcnt(3)
	v_mfma_f32_32x32x16_bf16 v[66:81], v[170:173], v[130:133], v[66:81]
	v_add_u32_e32 v144, 0xa500, v179
	ds_read2_b64 v[170:173], v144 offset1:1
	s_waitcnt lgkmcnt(3)
	v_mfma_f32_32x32x16_bf16 v[66:81], v[192:195], v[134:137], v[66:81]
	v_add_u32_e32 v144, 0xa520, v179
	ds_read2_b64 v[192:195], v144 offset1:1
	s_waitcnt lgkmcnt(3)
	v_mfma_f32_32x32x16_bf16 v[66:81], v[196:199], v[138:141], v[66:81]
	v_add_u32_e32 v144, 0xa540, v179
	ds_read2_b64 v[196:199], v144 offset1:1
	s_waitcnt lgkmcnt(3)
	v_mfma_f32_32x32x16_bf16 v[66:81], v[218:221], v[166:169], v[66:81]
	v_add_u32_e32 v144, 0xa560, v179
	ds_read2_b64 v[218:221], v144 offset1:1
	s_waitcnt lgkmcnt(3)
	v_mfma_f32_32x32x16_bf16 v[82:97], v[170:173], v[130:133], v[82:97]
	v_add_u32_e32 v144, 0xc600, v179
	ds_read2_b64 v[170:173], v144 offset1:1
	s_waitcnt lgkmcnt(3)
	v_mfma_f32_32x32x16_bf16 v[82:97], v[192:195], v[134:137], v[82:97]
	v_add_u32_e32 v144, 0xc620, v179
	ds_read2_b64 v[192:195], v144 offset1:1
	s_waitcnt lgkmcnt(3)
	v_mfma_f32_32x32x16_bf16 v[82:97], v[196:199], v[138:141], v[82:97]
	v_add_u32_e32 v144, 0xc640, v179
	ds_read2_b64 v[196:199], v144 offset1:1
	s_waitcnt lgkmcnt(3)
	v_mfma_f32_32x32x16_bf16 v[82:97], v[218:221], v[166:169], v[82:97]
	v_add_u32_e32 v144, 0xc660, v179
	ds_read2_b64 v[218:221], v144 offset1:1
	s_waitcnt lgkmcnt(3)
	v_mfma_f32_32x32x16_bf16 v[98:113], v[170:173], v[130:133], v[98:113]
	v_add_u32_e32 v144, 0xe700, v179
	ds_read2_b64 v[170:173], v144 offset1:1
	s_waitcnt lgkmcnt(3)
	v_mfma_f32_32x32x16_bf16 v[98:113], v[192:195], v[134:137], v[98:113]
	v_add_u32_e32 v144, 0xe720, v179
	ds_read2_b64 v[192:195], v144 offset1:1
	s_waitcnt lgkmcnt(3)
	v_mfma_f32_32x32x16_bf16 v[98:113], v[196:199], v[138:141], v[98:113]
	v_add_u32_e32 v144, 0xe740, v179
	ds_read2_b64 v[196:199], v144 offset1:1
	s_waitcnt lgkmcnt(3)
	v_mfma_f32_32x32x16_bf16 v[98:113], v[218:221], v[166:169], v[98:113]
	v_add_u32_e32 v144, 0xe760, v179
	ds_read2_b64 v[218:221], v144 offset1:1
	s_waitcnt lgkmcnt(3)
	v_mfma_f32_32x32x16_bf16 v[114:129], v[170:173], v[130:133], v[114:129]
	s_waitcnt lgkmcnt(2)
	v_mfma_f32_32x32x16_bf16 v[114:129], v[192:195], v[134:137], v[114:129]
	s_waitcnt lgkmcnt(1)
	v_mfma_f32_32x32x16_bf16 v[114:129], v[196:199], v[138:141], v[114:129]
	s_waitcnt lgkmcnt(0)
	v_mfma_f32_32x32x16_bf16 v[114:129], v[218:221], v[166:169], v[114:129]
	v_fmamk_f32 v134, v191, 0x42800000, v190
	v_fmamk_f32 v135, v191, 0x42820000, v190
	v_exp_f32_e32 v134, v134
	v_exp_f32_e32 v135, v135
	v_fmamk_f32 v138, v191, 0x42a00000, v190
	v_fmamk_f32 v139, v191, 0x42a20000, v190
	v_exp_f32_e32 v138, v138
	v_exp_f32_e32 v139, v139
	v_fmamk_f32 v144, v191, 0x42c00000, v190
	v_fmamk_f32 v145, v191, 0x42c20000, v190
	v_exp_f32_e32 v144, v144
	v_exp_f32_e32 v145, v145
	v_fmamk_f32 v153, v191, 0x42e00000, v190
	s_waitcnt vmcnt(0)
	v_mov_b32_e32 v130, v234
	v_mov_b32_e32 v131, v235
	v_mov_b32_e32 v132, v236
	v_mov_b32_e32 v133, v237
	v_lshlrev_b32_e32 v136, 16, v130
	v_and_b32_e32 v137, 0xffff0000, v130
	v_pk_mul_f32 v[134:135], v[134:135], v[136:137]
	v_lshlrev_b32_e32 v136, 16, v131
	v_cvt_pk_bf16_f32 v130, v134, v135
	v_fmamk_f32 v134, v191, 0x42840000, v190
	v_fmamk_f32 v135, v191, 0x42860000, v190
	v_exp_f32_e32 v134, v134
	v_exp_f32_e32 v135, v135
	v_and_b32_e32 v137, 0xffff0000, v131
	v_pk_mul_f32 v[134:135], v[134:135], v[136:137]
	s_nop 0
	v_cvt_pk_bf16_f32 v131, v134, v135
	v_fmamk_f32 v134, v191, 0x42880000, v190
	v_fmamk_f32 v135, v191, 0x428a0000, v190
	v_exp_f32_e32 v134, v134
	v_exp_f32_e32 v135, v135
	v_lshlrev_b32_e32 v136, 16, v132
	v_and_b32_e32 v137, 0xffff0000, v132
	v_pk_mul_f32 v[134:135], v[134:135], v[136:137]
	s_nop 0
	v_cvt_pk_bf16_f32 v132, v134, v135
	v_fmamk_f32 v134, v191, 0x428c0000, v190
	v_fmamk_f32 v135, v191, 0x428e0000, v190
	v_exp_f32_e32 v134, v134
	v_exp_f32_e32 v135, v135
	v_lshlrev_b32_e32 v136, 16, v133
	v_and_b32_e32 v137, 0xffff0000, v133
	v_pk_mul_f32 v[134:135], v[134:135], v[136:137]
	s_nop 0
	v_cvt_pk_bf16_f32 v133, v134, v135
	s_waitcnt vmcnt(0)
	v_mov_b32_e32 v134, v238
	v_mov_b32_e32 v135, v239
	v_mov_b32_e32 v136, v240
	v_mov_b32_e32 v137, v241
	v_lshlrev_b32_e32 v140, 16, v134
	v_and_b32_e32 v141, 0xffff0000, v134
	v_pk_mul_f32 v[138:139], v[138:139], v[140:141]
	v_lshlrev_b32_e32 v140, 16, v135
	v_cvt_pk_bf16_f32 v134, v138, v139
	v_fmamk_f32 v138, v191, 0x42a40000, v190
	v_fmamk_f32 v139, v191, 0x42a60000, v190
	v_exp_f32_e32 v138, v138
	v_exp_f32_e32 v139, v139
	v_and_b32_e32 v141, 0xffff0000, v135
	v_pk_mul_f32 v[138:139], v[138:139], v[140:141]
	s_nop 0
	v_cvt_pk_bf16_f32 v135, v138, v139
	v_fmamk_f32 v138, v191, 0x42a80000, v190
	v_fmamk_f32 v139, v191, 0x42aa0000, v190
	v_exp_f32_e32 v138, v138
	v_exp_f32_e32 v139, v139
	v_lshlrev_b32_e32 v140, 16, v136
	v_and_b32_e32 v141, 0xffff0000, v136
	v_pk_mul_f32 v[138:139], v[138:139], v[140:141]
	s_nop 0
	v_cvt_pk_bf16_f32 v136, v138, v139
	v_fmamk_f32 v138, v191, 0x42ac0000, v190
	v_fmamk_f32 v139, v191, 0x42ae0000, v190
	v_exp_f32_e32 v138, v138
	v_exp_f32_e32 v139, v139
	v_lshlrev_b32_e32 v140, 16, v137
	v_and_b32_e32 v141, 0xffff0000, v137
	v_pk_mul_f32 v[138:139], v[138:139], v[140:141]
	s_nop 0
	v_cvt_pk_bf16_f32 v137, v138, v139
	s_waitcnt vmcnt(0)
	v_mov_b32_e32 v138, v242
	v_mov_b32_e32 v139, v243
	v_mov_b32_e32 v140, v244
	v_mov_b32_e32 v141, v245
	v_lshlrev_b32_e32 v166, 16, v138
	v_and_b32_e32 v167, 0xffff0000, v138
	v_pk_mul_f32 v[144:145], v[144:145], v[166:167]
	v_lshlrev_b32_e32 v166, 16, v139
	v_cvt_pk_bf16_f32 v138, v144, v145
	v_fmamk_f32 v144, v191, 0x42c40000, v190
	v_fmamk_f32 v145, v191, 0x42c60000, v190
	v_exp_f32_e32 v144, v144
	v_exp_f32_e32 v145, v145
	v_and_b32_e32 v167, 0xffff0000, v139
	v_pk_mul_f32 v[144:145], v[144:145], v[166:167]
	s_nop 0
	v_cvt_pk_bf16_f32 v139, v144, v145
	v_fmamk_f32 v144, v191, 0x42c80000, v190
	v_fmamk_f32 v145, v191, 0x42ca0000, v190
	v_exp_f32_e32 v144, v144
	v_exp_f32_e32 v145, v145
	v_lshlrev_b32_e32 v166, 16, v140
	v_and_b32_e32 v167, 0xffff0000, v140
	v_pk_mul_f32 v[144:145], v[144:145], v[166:167]
	s_nop 0
	v_cvt_pk_bf16_f32 v140, v144, v145
	v_fmamk_f32 v144, v191, 0x42cc0000, v190
	v_fmamk_f32 v145, v191, 0x42ce0000, v190
	v_exp_f32_e32 v144, v144
	v_exp_f32_e32 v145, v145
	v_lshlrev_b32_e32 v166, 16, v141
	v_and_b32_e32 v167, 0xffff0000, v141
	v_pk_mul_f32 v[144:145], v[144:145], v[166:167]
	s_nop 0
	v_cvt_pk_bf16_f32 v141, v144, v145
	v_exp_f32_e32 v166, v153
	v_fmamk_f32 v153, v191, 0x42e20000, v190
	v_exp_f32_e32 v167, v153
	v_fmamk_f32 v153, v191, 0x42e40000, v190
	s_waitcnt vmcnt(0)
	v_mov_b32_e32 v142, v246
	v_mov_b32_e32 v143, v247
	v_mov_b32_e32 v144, v248
	v_mov_b32_e32 v145, v249
	v_lshlrev_b32_e32 v168, 16, v142
	v_and_b32_e32 v169, 0xffff0000, v142
	v_pk_mul_f32 v[166:167], v[166:167], v[168:169]
	v_lshlrev_b32_e32 v168, 16, v143
	v_cvt_pk_bf16_f32 v142, v166, v167
	v_exp_f32_e32 v166, v153
	v_fmamk_f32 v153, v191, 0x42e60000, v190
	v_exp_f32_e32 v167, v153
	v_and_b32_e32 v169, 0xffff0000, v143
	v_fmamk_f32 v153, v191, 0x42e80000, v190
	v_pk_mul_f32 v[166:167], v[166:167], v[168:169]
	s_nop 0
	v_cvt_pk_bf16_f32 v143, v166, v167
	v_exp_f32_e32 v166, v153
	v_fmamk_f32 v153, v191, 0x42ea0000, v190
	v_exp_f32_e32 v167, v153
	v_lshlrev_b32_e32 v168, 16, v144
	v_and_b32_e32 v169, 0xffff0000, v144
	v_fmamk_f32 v153, v191, 0x42ec0000, v190
	v_pk_mul_f32 v[166:167], v[166:167], v[168:169]
	v_fmac_f32_e32 v190, 0x42ee0000, v191
	v_cvt_pk_bf16_f32 v144, v166, v167
	v_exp_f32_e32 v166, v153
	v_exp_f32_e32 v167, v190
	v_lshlrev_b32_e32 v168, 16, v145
	v_and_b32_e32 v169, 0xffff0000, v145
	v_pk_mul_f32 v[166:167], v[166:167], v[168:169]
	s_nop 0
	v_cvt_pk_bf16_f32 v145, v166, v167
	ds_read2_b64 v[166:169], v179 offset0:16 offset1:17
	ds_read2_b64 v[170:173], v179 offset0:20 offset1:21
	ds_read2_b64 v[190:193], v179 offset0:24 offset1:25
	ds_read2_b64 v[194:197], v179 offset0:28 offset1:29
	s_waitcnt lgkmcnt(3)
	v_mfma_f32_32x32x16_bf16 v[2:17], v[166:169], v[130:133], v[2:17]
	v_add_u32_e32 v153, 0x2180, v179
	ds_read2_b64 v[166:169], v153 offset1:1
	s_waitcnt lgkmcnt(3)
	v_mfma_f32_32x32x16_bf16 v[2:17], v[170:173], v[134:137], v[2:17]
	v_add_u32_e32 v153, 0x21a0, v179
	ds_read2_b64 v[170:173], v153 offset1:1
	s_waitcnt lgkmcnt(3)
	v_mfma_f32_32x32x16_bf16 v[2:17], v[190:193], v[138:141], v[2:17]
	v_add_u32_e32 v153, 0x21c0, v179
	ds_read2_b64 v[190:193], v153 offset1:1
	s_waitcnt lgkmcnt(3)
	v_mfma_f32_32x32x16_bf16 v[2:17], v[194:197], v[142:145], v[2:17]
	v_add_u32_e32 v153, 0x21e0, v179
	ds_read2_b64 v[194:197], v153 offset1:1
	s_waitcnt lgkmcnt(3)
	v_mfma_f32_32x32x16_bf16 v[18:33], v[166:169], v[130:133], v[18:33]
	v_add_u32_e32 v153, 0x4280, v179
	ds_read2_b64 v[166:169], v153 offset1:1
	s_waitcnt lgkmcnt(3)
	v_mfma_f32_32x32x16_bf16 v[18:33], v[170:173], v[134:137], v[18:33]
	v_add_u32_e32 v153, 0x42a0, v179
	ds_read2_b64 v[170:173], v153 offset1:1
	s_waitcnt lgkmcnt(3)
	v_mfma_f32_32x32x16_bf16 v[18:33], v[190:193], v[138:141], v[18:33]
	v_add_u32_e32 v153, 0x42c0, v179
	ds_read2_b64 v[190:193], v153 offset1:1
	s_waitcnt lgkmcnt(3)
	v_mfma_f32_32x32x16_bf16 v[18:33], v[194:197], v[142:145], v[18:33]
	v_add_u32_e32 v153, 0x42e0, v179
	ds_read2_b64 v[194:197], v153 offset1:1
	s_waitcnt lgkmcnt(3)
	v_mfma_f32_32x32x16_bf16 v[34:49], v[166:169], v[130:133], v[34:49]
	v_add_u32_e32 v153, 0x6380, v179
	ds_read2_b64 v[166:169], v153 offset1:1
	s_waitcnt lgkmcnt(3)
	v_mfma_f32_32x32x16_bf16 v[34:49], v[170:173], v[134:137], v[34:49]
	v_add_u32_e32 v153, 0x63a0, v179
	ds_read2_b64 v[170:173], v153 offset1:1
	s_waitcnt lgkmcnt(3)
	v_mfma_f32_32x32x16_bf16 v[34:49], v[190:193], v[138:141], v[34:49]
	v_add_u32_e32 v153, 0x63c0, v179
	ds_read2_b64 v[190:193], v153 offset1:1
	s_waitcnt lgkmcnt(3)
	v_mfma_f32_32x32x16_bf16 v[34:49], v[194:197], v[142:145], v[34:49]
	v_add_u32_e32 v153, 0x63e0, v179
	ds_read2_b64 v[194:197], v153 offset1:1
	s_waitcnt lgkmcnt(3)
	v_mfma_f32_32x32x16_bf16 v[50:65], v[166:169], v[130:133], v[50:65]
	v_add_u32_e32 v153, 0x8480, v179
	ds_read2_b64 v[166:169], v153 offset1:1
	s_waitcnt lgkmcnt(3)
	v_mfma_f32_32x32x16_bf16 v[50:65], v[170:173], v[134:137], v[50:65]
	v_add_u32_e32 v153, 0x84a0, v179
	ds_read2_b64 v[170:173], v153 offset1:1
	s_waitcnt lgkmcnt(3)
	v_mfma_f32_32x32x16_bf16 v[50:65], v[190:193], v[138:141], v[50:65]
	v_add_u32_e32 v153, 0x84c0, v179
	ds_read2_b64 v[190:193], v153 offset1:1
	s_waitcnt lgkmcnt(3)
	v_mfma_f32_32x32x16_bf16 v[50:65], v[194:197], v[142:145], v[50:65]
	v_add_u32_e32 v153, 0x84e0, v179
	ds_read2_b64 v[194:197], v153 offset1:1
	s_waitcnt lgkmcnt(3)
	v_mfma_f32_32x32x16_bf16 v[66:81], v[166:169], v[130:133], v[66:81]
	v_add_u32_e32 v153, 0xa580, v179
	ds_read2_b64 v[166:169], v153 offset1:1
	s_waitcnt lgkmcnt(3)
	v_mfma_f32_32x32x16_bf16 v[66:81], v[170:173], v[134:137], v[66:81]
	v_add_u32_e32 v153, 0xa5a0, v179
	ds_read2_b64 v[170:173], v153 offset1:1
	s_waitcnt lgkmcnt(3)
	v_mfma_f32_32x32x16_bf16 v[66:81], v[190:193], v[138:141], v[66:81]
	v_add_u32_e32 v153, 0xa5c0, v179
	ds_read2_b64 v[190:193], v153 offset1:1
	s_waitcnt lgkmcnt(3)
	v_mfma_f32_32x32x16_bf16 v[66:81], v[194:197], v[142:145], v[66:81]
	v_add_u32_e32 v153, 0xa5e0, v179
	ds_read2_b64 v[194:197], v153 offset1:1
	s_waitcnt lgkmcnt(3)
	v_mfma_f32_32x32x16_bf16 v[82:97], v[166:169], v[130:133], v[82:97]
	v_add_u32_e32 v153, 0xc680, v179
	ds_read2_b64 v[166:169], v153 offset1:1
	s_waitcnt lgkmcnt(3)
	v_mfma_f32_32x32x16_bf16 v[82:97], v[170:173], v[134:137], v[82:97]
	v_add_u32_e32 v153, 0xc6a0, v179
	ds_read2_b64 v[170:173], v153 offset1:1
	s_waitcnt lgkmcnt(3)
	v_mfma_f32_32x32x16_bf16 v[82:97], v[190:193], v[138:141], v[82:97]
	v_add_u32_e32 v153, 0xc6c0, v179
	ds_read2_b64 v[190:193], v153 offset1:1
	s_waitcnt lgkmcnt(3)
	v_mfma_f32_32x32x16_bf16 v[82:97], v[194:197], v[142:145], v[82:97]
	v_add_u32_e32 v153, 0xc6e0, v179
	ds_read2_b64 v[194:197], v153 offset1:1
	s_waitcnt lgkmcnt(3)
	v_mfma_f32_32x32x16_bf16 v[98:113], v[166:169], v[130:133], v[98:113]
	v_add_u32_e32 v153, 0xe780, v179
	ds_read2_b64 v[166:169], v153 offset1:1
	s_waitcnt lgkmcnt(3)
	v_mfma_f32_32x32x16_bf16 v[98:113], v[170:173], v[134:137], v[98:113]
	v_add_u32_e32 v153, 0xe7a0, v179
	ds_read2_b64 v[170:173], v153 offset1:1
	s_waitcnt lgkmcnt(3)
	v_mfma_f32_32x32x16_bf16 v[98:113], v[190:193], v[138:141], v[98:113]
	v_add_u32_e32 v153, 0xe7c0, v179
	ds_read2_b64 v[190:193], v153 offset1:1
	s_waitcnt lgkmcnt(3)
	v_mfma_f32_32x32x16_bf16 v[98:113], v[194:197], v[142:145], v[98:113]
	v_add_u32_e32 v153, 0xe7e0, v179
	ds_read2_b64 v[194:197], v153 offset1:1
	s_waitcnt lgkmcnt(3)
	v_mfma_f32_32x32x16_bf16 v[114:129], v[166:169], v[130:133], v[114:129]
	s_waitcnt lgkmcnt(2)
	v_mfma_f32_32x32x16_bf16 v[114:129], v[170:173], v[134:137], v[114:129]
	s_waitcnt lgkmcnt(1)
	v_mfma_f32_32x32x16_bf16 v[114:129], v[190:193], v[138:141], v[114:129]
	s_waitcnt lgkmcnt(0)
	v_mfma_f32_32x32x16_bf16 v[114:129], v[194:197], v[142:145], v[114:129]
	s_add_i32 s66, s66, 1
	s_add_i32 s67, s67, -1
	s_cmp_eq_u32 s67, -1
	s_cbranch_scc0 .LBB0_327
	s_and_b64 vcc, exec, s[4:5]
	s_mov_b64 s[4:5], -1
	s_cbranch_vccnz .LBB0_330
	s_mov_b64 s[4:5], 0
